# v22 + scalarized (saddr) LDS-DMA addressing also in the in-proj, out-proj, FFN-down (3 instances) K-loops; loop heads kept at baseline byte phase
# baseline (speedup 1.0000x reference)
.LBB0_246:
	s_add_u32 s3, s34, 0xfff80080
	s_addc_u32 s6, s35, -1
	s_add_i32 s7, 0, 0x10000
	s_cmp_eq_u32 s2, 28
	s_cselect_b32 s43, s15, s6
	s_cselect_b32 s42, s47, s3
	s_cselect_b32 s39, s13, s50
	s_cselect_b32 s38, s48, s49
	s_add_i32 s3, 0, 0x14000
	v_add_u32_e32 v156, s7, v145
	v_add_u32_e32 v172, s3, v145
	ds_read_b128 v[140:143], v156
	ds_read_b128 v[148:151], v156 offset:1024
	ds_read_b128 v[152:155], v156 offset:2048
	ds_read_b128 v[156:159], v156 offset:3072
	ds_read_b128 v[160:163], v172
	ds_read_b128 v[164:167], v172 offset:1024
	ds_read_b128 v[168:171], v172 offset:2048
	ds_read_b128 v[172:175], v172 offset:3072
	s_add_i32 m0, s18, 0xc000
	ds_read_b128 v[182:185], v147
	ds_read_b128 v[186:189], v147 offset:1024
	ds_read_b128 v[190:193], v147 offset:2048
	ds_read_b128 v[214:217], v147 offset:3072
	ds_read_b128 v[218:221], v147 offset:4096
	ds_read_b128 v[222:225], v147 offset:5120
	ds_read_b128 v[226:229], v147 offset:6144
	ds_read_b128 v[230:233], v147 offset:7168
	global_load_lds_dwordx4 v136, s[34:35]
	s_add_i32 m0, s18, 0xe000
	s_nop 0
	global_load_lds_dwordx4 v138, s[34:35]
	s_waitcnt vmcnt(8)
	s_waitcnt lgkmcnt(0)
	s_barrier
	s_setprio 1
	s_waitcnt lgkmcnt(0)
	v_mfma_f32_16x16x32_bf16 v[126:129], v[140:143], v[182:185], v[126:129]
	v_mfma_f32_16x16x32_bf16 v[122:125], v[152:155], v[182:185], v[122:125]
	v_mfma_f32_16x16x32_bf16 v[118:121], v[140:143], v[190:193], v[118:121]
	v_mfma_f32_16x16x32_bf16 v[110:113], v[152:155], v[190:193], v[110:113]
	v_mfma_f32_16x16x32_bf16 v[102:105], v[140:143], v[218:221], v[102:105]
	v_mfma_f32_16x16x32_bf16 v[92:95], v[152:155], v[218:221], v[92:95]
	v_mfma_f32_16x16x32_bf16 v[84:87], v[140:143], v[226:229], v[84:87]
	v_mfma_f32_16x16x32_bf16 v[76:79], v[152:155], v[226:229], v[76:79]
	v_mfma_f32_16x16x32_bf16 v[126:129], v[148:151], v[186:189], v[126:129]
	v_mfma_f32_16x16x32_bf16 v[122:125], v[156:159], v[186:189], v[122:125]
	v_mfma_f32_16x16x32_bf16 v[118:121], v[148:151], v[214:217], v[118:121]
	v_mfma_f32_16x16x32_bf16 v[110:113], v[156:159], v[214:217], v[110:113]
	v_mfma_f32_16x16x32_bf16 v[102:105], v[148:151], v[222:225], v[102:105]
	v_mfma_f32_16x16x32_bf16 v[92:95], v[156:159], v[222:225], v[92:95]
	v_mfma_f32_16x16x32_bf16 v[84:87], v[148:151], v[230:233], v[84:87]
	v_mfma_f32_16x16x32_bf16 v[76:79], v[156:159], v[230:233], v[76:79]
	s_setprio 0
	s_setprio 1
	v_mfma_f32_16x16x32_bf16 v[114:117], v[160:163], v[182:185], v[114:117]
	v_mfma_f32_16x16x32_bf16 v[106:109], v[168:171], v[182:185], v[106:109]
	v_mfma_f32_16x16x32_bf16 v[98:101], v[160:163], v[190:193], v[98:101]
	v_mfma_f32_16x16x32_bf16 v[88:91], v[168:171], v[190:193], v[88:91]
	v_mfma_f32_16x16x32_bf16 v[80:83], v[160:163], v[218:221], v[80:83]
	v_mfma_f32_16x16x32_bf16 v[72:75], v[168:171], v[218:221], v[72:75]
	v_mfma_f32_16x16x32_bf16 v[68:71], v[160:163], v[226:229], v[68:71]
	v_mfma_f32_16x16x32_bf16 v[64:67], v[168:171], v[226:229], v[64:67]
	v_mfma_f32_16x16x32_bf16 v[114:117], v[164:167], v[186:189], v[114:117]
	v_mfma_f32_16x16x32_bf16 v[106:109], v[172:175], v[186:189], v[106:109]
	v_mfma_f32_16x16x32_bf16 v[98:101], v[164:167], v[214:217], v[98:101]
	v_mfma_f32_16x16x32_bf16 v[88:91], v[172:175], v[214:217], v[88:91]
	v_mfma_f32_16x16x32_bf16 v[80:83], v[164:167], v[222:225], v[80:83]
	v_mfma_f32_16x16x32_bf16 v[72:75], v[172:175], v[222:225], v[72:75]
	v_mfma_f32_16x16x32_bf16 v[68:71], v[164:167], v[230:233], v[68:71]
	v_mfma_f32_16x16x32_bf16 v[64:67], v[172:175], v[230:233], v[64:67]
	s_setprio 0
	s_barrier
	s_add_i32 s6, s7, s17
	s_mov_b32 m0, s6
	ds_read_b128 v[182:185], v147 offset:16384
	ds_read_b128 v[186:189], v147 offset:17408
	ds_read_b128 v[190:193], v147 offset:18432
	ds_read_b128 v[214:217], v147 offset:19456
	ds_read_b128 v[218:221], v147 offset:20480
	ds_read_b128 v[222:225], v147 offset:21504
	ds_read_b128 v[226:229], v147 offset:22528
	ds_read_b128 v[230:233], v147 offset:23552
	global_load_lds_dwordx4 v96, s[38:39]
	s_add_i32 m0, s6, 0x2000
	s_add_u32 s6, s38, 0x80000
	s_addc_u32 s7, s39, 0
	s_add_i32 s3, s3, s17
	global_load_lds_dwordx4 v130, s[38:39]
	s_mov_b32 m0, s3
	s_nop 0
	global_load_lds_dwordx4 v96, s[6:7]
	s_add_i32 m0, s3, 0x2000
	s_nop 0
	global_load_lds_dwordx4 v130, s[6:7]
	s_mov_b32 m0, s18
	s_nop 0
	global_load_lds_dwordx4 v134, s[42:43]
	s_mov_b32 m0, s19
	s_nop 0
	global_load_lds_dwordx4 v132, s[42:43]
	s_waitcnt vmcnt(8)
	s_waitcnt lgkmcnt(0)
	s_barrier
	s_setprio 1
	s_waitcnt lgkmcnt(0)
	v_mfma_f32_16x16x32_bf16 v[60:63], v[140:143], v[182:185], v[60:63]
	v_mfma_f32_16x16x32_bf16 v[56:59], v[152:155], v[182:185], v[56:59]
	v_mfma_f32_16x16x32_bf16 v[52:55], v[140:143], v[190:193], v[52:55]
	v_mfma_f32_16x16x32_bf16 v[44:47], v[152:155], v[190:193], v[44:47]
	v_mfma_f32_16x16x32_bf16 v[36:39], v[140:143], v[218:221], v[36:39]
	v_mfma_f32_16x16x32_bf16 v[28:31], v[152:155], v[218:221], v[28:31]
	v_mfma_f32_16x16x32_bf16 v[20:23], v[140:143], v[226:229], v[20:23]
	v_mfma_f32_16x16x32_bf16 v[12:15], v[152:155], v[226:229], v[12:15]
	v_mfma_f32_16x16x32_bf16 v[60:63], v[148:151], v[186:189], v[60:63]
	v_mfma_f32_16x16x32_bf16 v[56:59], v[156:159], v[186:189], v[56:59]
	v_mfma_f32_16x16x32_bf16 v[52:55], v[148:151], v[214:217], v[52:55]
	v_mfma_f32_16x16x32_bf16 v[44:47], v[156:159], v[214:217], v[44:47]
	v_mfma_f32_16x16x32_bf16 v[36:39], v[148:151], v[222:225], v[36:39]
	v_mfma_f32_16x16x32_bf16 v[28:31], v[156:159], v[222:225], v[28:31]
	v_mfma_f32_16x16x32_bf16 v[20:23], v[148:151], v[230:233], v[20:23]
	v_mfma_f32_16x16x32_bf16 v[12:15], v[156:159], v[230:233], v[12:15]
	s_setprio 0
	s_setprio 1
	v_mfma_f32_16x16x32_bf16 v[48:51], v[160:163], v[182:185], v[48:51]
	v_mfma_f32_16x16x32_bf16 v[40:43], v[168:171], v[182:185], v[40:43]
	v_mfma_f32_16x16x32_bf16 v[32:35], v[160:163], v[190:193], v[32:35]
	v_mfma_f32_16x16x32_bf16 v[24:27], v[168:171], v[190:193], v[24:27]
	v_mfma_f32_16x16x32_bf16 v[16:19], v[160:163], v[218:221], v[16:19]
	v_mfma_f32_16x16x32_bf16 v[8:11], v[168:171], v[218:221], v[8:11]
	v_mfma_f32_16x16x32_bf16 v[4:7], v[160:163], v[226:229], v[4:7]
	v_mfma_f32_16x16x32_bf16 v[0:3], v[168:171], v[226:229], v[0:3]
	v_mfma_f32_16x16x32_bf16 v[48:51], v[164:167], v[186:189], v[48:51]
	v_mfma_f32_16x16x32_bf16 v[40:43], v[172:175], v[186:189], v[40:43]
	v_mfma_f32_16x16x32_bf16 v[32:35], v[164:167], v[214:217], v[32:35]
	v_mfma_f32_16x16x32_bf16 v[24:27], v[172:175], v[214:217], v[24:27]
	v_mfma_f32_16x16x32_bf16 v[16:19], v[164:167], v[222:225], v[16:19]
	v_mfma_f32_16x16x32_bf16 v[8:11], v[172:175], v[222:225], v[8:11]
	v_mfma_f32_16x16x32_bf16 v[4:7], v[164:167], v[230:233], v[4:7]
	v_mfma_f32_16x16x32_bf16 v[0:3], v[172:175], v[230:233], v[0:3]
	s_setprio 0
	s_barrier
	s_add_i32 s3, 0, 0x18000
	s_add_i32 s51, 0, 0x1c000
	v_add_u32_e32 v156, s3, v145
	v_add_u32_e32 v172, s51, v145
	ds_read_b128 v[140:143], v156
	ds_read_b128 v[148:151], v156 offset:1024
	ds_read_b128 v[152:155], v156 offset:2048
	ds_read_b128 v[156:159], v156 offset:3072
	ds_read_b128 v[160:163], v172
	ds_read_b128 v[164:167], v172 offset:1024
	ds_read_b128 v[168:171], v172 offset:2048
	ds_read_b128 v[172:175], v172 offset:3072
	s_add_u32 s6, s42, 0x80000
	s_addc_u32 s7, s43, 0
	s_mov_b32 m0, s20
	ds_read_b128 v[182:185], v147 offset:32768
	ds_read_b128 v[186:189], v147 offset:33792
	ds_read_b128 v[190:193], v147 offset:34816
	ds_read_b128 v[214:217], v147 offset:35840
	ds_read_b128 v[218:221], v147 offset:36864
	ds_read_b128 v[222:225], v147 offset:37888
	ds_read_b128 v[226:229], v147 offset:38912
	ds_read_b128 v[230:233], v147 offset:39936
	global_load_lds_dwordx4 v134, s[6:7]
	s_mov_b32 m0, s36
	s_nop 0
	global_load_lds_dwordx4 v132, s[6:7]
	s_waitcnt vmcnt(8)
	s_waitcnt lgkmcnt(0)
	s_barrier
	s_setprio 1
	s_waitcnt lgkmcnt(0)
	v_mfma_f32_16x16x32_bf16 v[126:129], v[140:143], v[182:185], v[126:129]
	v_mfma_f32_16x16x32_bf16 v[122:125], v[152:155], v[182:185], v[122:125]
	v_mfma_f32_16x16x32_bf16 v[118:121], v[140:143], v[190:193], v[118:121]
	v_mfma_f32_16x16x32_bf16 v[110:113], v[152:155], v[190:193], v[110:113]
	v_mfma_f32_16x16x32_bf16 v[102:105], v[140:143], v[218:221], v[102:105]
	v_mfma_f32_16x16x32_bf16 v[92:95], v[152:155], v[218:221], v[92:95]
	v_mfma_f32_16x16x32_bf16 v[84:87], v[140:143], v[226:229], v[84:87]
	v_mfma_f32_16x16x32_bf16 v[76:79], v[152:155], v[226:229], v[76:79]
	v_mfma_f32_16x16x32_bf16 v[126:129], v[148:151], v[186:189], v[126:129]
	v_mfma_f32_16x16x32_bf16 v[122:125], v[156:159], v[186:189], v[122:125]
	v_mfma_f32_16x16x32_bf16 v[118:121], v[148:151], v[214:217], v[118:121]
	v_mfma_f32_16x16x32_bf16 v[110:113], v[156:159], v[214:217], v[110:113]
	v_mfma_f32_16x16x32_bf16 v[102:105], v[148:151], v[222:225], v[102:105]
	v_mfma_f32_16x16x32_bf16 v[92:95], v[156:159], v[222:225], v[92:95]
	v_mfma_f32_16x16x32_bf16 v[84:87], v[148:151], v[230:233], v[84:87]
	v_mfma_f32_16x16x32_bf16 v[76:79], v[156:159], v[230:233], v[76:79]
	s_setprio 0
	s_setprio 1
	v_mfma_f32_16x16x32_bf16 v[114:117], v[160:163], v[182:185], v[114:117]
	v_mfma_f32_16x16x32_bf16 v[106:109], v[168:171], v[182:185], v[106:109]
	v_mfma_f32_16x16x32_bf16 v[98:101], v[160:163], v[190:193], v[98:101]
	v_mfma_f32_16x16x32_bf16 v[88:91], v[168:171], v[190:193], v[88:91]
	v_mfma_f32_16x16x32_bf16 v[80:83], v[160:163], v[218:221], v[80:83]
	v_mfma_f32_16x16x32_bf16 v[72:75], v[168:171], v[218:221], v[72:75]
	v_mfma_f32_16x16x32_bf16 v[68:71], v[160:163], v[226:229], v[68:71]
	v_mfma_f32_16x16x32_bf16 v[64:67], v[168:171], v[226:229], v[64:67]
	v_mfma_f32_16x16x32_bf16 v[114:117], v[164:167], v[186:189], v[114:117]
	v_mfma_f32_16x16x32_bf16 v[106:109], v[172:175], v[186:189], v[106:109]
	v_mfma_f32_16x16x32_bf16 v[98:101], v[164:167], v[214:217], v[98:101]
	v_mfma_f32_16x16x32_bf16 v[88:91], v[172:175], v[214:217], v[88:91]
	v_mfma_f32_16x16x32_bf16 v[80:83], v[164:167], v[222:225], v[80:83]
	v_mfma_f32_16x16x32_bf16 v[72:75], v[172:175], v[222:225], v[72:75]
	v_mfma_f32_16x16x32_bf16 v[68:71], v[164:167], v[230:233], v[68:71]
	v_mfma_f32_16x16x32_bf16 v[64:67], v[172:175], v[230:233], v[64:67]
	s_setprio 0
	s_barrier
	s_add_i32 s3, s3, s17
	s_mov_b32 m0, s3
	ds_read_b128 v[182:185], v147 offset:49152
	ds_read_b128 v[186:189], v147 offset:50176
	ds_read_b128 v[190:193], v147 offset:51200
	ds_read_b128 v[214:217], v147 offset:52224
	ds_read_b128 v[218:221], v147 offset:53248
	ds_read_b128 v[222:225], v147 offset:54272
	ds_read_b128 v[226:229], v147 offset:55296
	ds_read_b128 v[230:233], v147 offset:56320
	s_add_u32 s100, s38, 0x80
	s_addc_u32 s101, s39, 0
	global_load_lds_dwordx4 v96, s[100:101]
	s_add_i32 m0, s3, 0x2000
	s_add_u32 s6, s38, 0x80080
	s_addc_u32 s7, s39, 0
	s_add_i32 s3, s51, s17
	global_load_lds_dwordx4 v130, s[100:101]
	s_mov_b32 m0, s3
	s_nop 0
	global_load_lds_dwordx4 v96, s[6:7]
	s_add_i32 m0, s3, 0x2000
	s_nop 0
	global_load_lds_dwordx4 v130, s[6:7]
	s_mov_b32 m0, s37
	s_nop 0
	s_add_u32 s100, s42, 0x80
	s_addc_u32 s101, s43, 0
	global_load_lds_dwordx4 v134, s[100:101]
	s_mov_b32 m0, s40
	s_nop 0
	global_load_lds_dwordx4 v132, s[100:101]
	s_waitcnt vmcnt(8)
	s_waitcnt lgkmcnt(0)
	s_barrier
	s_setprio 1
	s_waitcnt lgkmcnt(0)
	v_mfma_f32_16x16x32_bf16 v[60:63], v[140:143], v[182:185], v[60:63]
	v_mfma_f32_16x16x32_bf16 v[56:59], v[152:155], v[182:185], v[56:59]
	v_mfma_f32_16x16x32_bf16 v[52:55], v[140:143], v[190:193], v[52:55]
	v_mfma_f32_16x16x32_bf16 v[44:47], v[152:155], v[190:193], v[44:47]
	v_mfma_f32_16x16x32_bf16 v[36:39], v[140:143], v[218:221], v[36:39]
	v_mfma_f32_16x16x32_bf16 v[28:31], v[152:155], v[218:221], v[28:31]
	v_mfma_f32_16x16x32_bf16 v[20:23], v[140:143], v[226:229], v[20:23]
	v_mfma_f32_16x16x32_bf16 v[12:15], v[152:155], v[226:229], v[12:15]
	v_mfma_f32_16x16x32_bf16 v[60:63], v[148:151], v[186:189], v[60:63]
	v_mfma_f32_16x16x32_bf16 v[56:59], v[156:159], v[186:189], v[56:59]
	v_mfma_f32_16x16x32_bf16 v[52:55], v[148:151], v[214:217], v[52:55]
	v_mfma_f32_16x16x32_bf16 v[44:47], v[156:159], v[214:217], v[44:47]
	v_mfma_f32_16x16x32_bf16 v[36:39], v[148:151], v[222:225], v[36:39]
	v_mfma_f32_16x16x32_bf16 v[28:31], v[156:159], v[222:225], v[28:31]
	v_mfma_f32_16x16x32_bf16 v[20:23], v[148:151], v[230:233], v[20:23]
	v_mfma_f32_16x16x32_bf16 v[12:15], v[156:159], v[230:233], v[12:15]
	s_setprio 0
	s_setprio 1
	v_mfma_f32_16x16x32_bf16 v[48:51], v[160:163], v[182:185], v[48:51]
	v_mfma_f32_16x16x32_bf16 v[40:43], v[168:171], v[182:185], v[40:43]
	v_mfma_f32_16x16x32_bf16 v[32:35], v[160:163], v[190:193], v[32:35]
	v_mfma_f32_16x16x32_bf16 v[24:27], v[168:171], v[190:193], v[24:27]
	v_mfma_f32_16x16x32_bf16 v[16:19], v[160:163], v[218:221], v[16:19]
	v_mfma_f32_16x16x32_bf16 v[8:11], v[168:171], v[218:221], v[8:11]
	v_mfma_f32_16x16x32_bf16 v[4:7], v[160:163], v[226:229], v[4:7]
	v_mfma_f32_16x16x32_bf16 v[0:3], v[168:171], v[226:229], v[0:3]
	v_mfma_f32_16x16x32_bf16 v[48:51], v[164:167], v[186:189], v[48:51]
	v_mfma_f32_16x16x32_bf16 v[40:43], v[172:175], v[186:189], v[40:43]
	v_mfma_f32_16x16x32_bf16 v[32:35], v[164:167], v[214:217], v[32:35]
	v_mfma_f32_16x16x32_bf16 v[24:27], v[172:175], v[214:217], v[24:27]
	v_mfma_f32_16x16x32_bf16 v[16:19], v[164:167], v[222:225], v[16:19]
	v_mfma_f32_16x16x32_bf16 v[8:11], v[172:175], v[222:225], v[8:11]
	v_mfma_f32_16x16x32_bf16 v[4:7], v[164:167], v[230:233], v[4:7]
	v_mfma_f32_16x16x32_bf16 v[0:3], v[172:175], v[230:233], v[0:3]
	s_setprio 0
	s_barrier
	s_add_i32 s2, s2, 2
	s_add_u32 s34, s34, 0x100
	s_addc_u32 s35, s35, 0
	s_add_u32 s49, s49, 0x100
	s_addc_u32 s50, s50, 0
	s_cmp_gt_u32 s2, 29
	s_cbranch_scc0 .LBB0_246
	s_nop 0
	s_nop 0
	s_nop 0
	s_nop 0
	s_nop 0
	s_nop 0
	s_nop 0
	s_nop 0
	s_nop 0
	s_and_b64 vcc, exec, s[10:11]
	s_cbranch_vccz .LBB0_249
	s_barrier

.LBB0_993:
	s_add_u32 s3, s24, s46
	s_addc_u32 s6, s25, s47
	s_add_u32 s3, s3, 0x100
	s_addc_u32 s6, s6, 0
	s_add_u32 s48, s59, s46
	s_addc_u32 s49, s60, s47
	s_add_i32 s63, 0, 0x10000
	s_cmpk_eq_i32 s46, 0xf00
	s_cselect_b32 s51, s23, s6
	s_cselect_b32 s50, s61, s3
	v_add_u32_e32 v146, s63, v144
	s_cselect_b32 s49, s15, s49
	s_cselect_b32 s48, s62, s48
	s_add_i32 s3, 0, 0x14000
	ds_read_b128 v[154:157], v146
	ds_read_b128 v[158:161], v146 offset:1024
	ds_read_b128 v[162:165], v146 offset:2048
	ds_read_b128 v[166:169], v146 offset:3072
	v_add_u32_e32 v146, s3, v144
	ds_read_b128 v[174:177], v146
	ds_read_b128 v[178:181], v146 offset:1024
	ds_read_b128 v[182:185], v146 offset:2048
	ds_read_b128 v[186:189], v146 offset:3072
	v_lshl_add_u64 v[146:147], v[140:141], 0, s[46:47]
	s_add_i32 m0, s17, 0xc000
	ds_read_b128 v[190:193], v145
	ds_read_b128 v[202:205], v145 offset:1024
	ds_read_b128 v[206:209], v145 offset:2048
	ds_read_b128 v[214:217], v145 offset:3072
	ds_read_b128 v[218:221], v145 offset:4096
	ds_read_b128 v[222:225], v145 offset:5120
	ds_read_b128 v[226:229], v145 offset:6144
	ds_read_b128 v[230:233], v145 offset:7168
	global_load_lds_dwordx4 v[146:147], off
	v_lshl_add_u64 v[146:147], v[142:143], 0, s[46:47]
	s_add_i32 m0, s17, 0xe000
	s_nop 0
	global_load_lds_dwordx4 v[146:147], off
	s_waitcnt vmcnt(8)
	s_waitcnt lgkmcnt(0)
	s_barrier
	s_setprio 1
	s_waitcnt lgkmcnt(0)
	v_mfma_f32_16x16x32_bf16 v[110:113], v[154:157], v[190:193], v[110:113]
	v_mfma_f32_16x16x32_bf16 v[106:109], v[162:165], v[190:193], v[106:109]
	v_mfma_f32_16x16x32_bf16 v[118:121], v[154:157], v[206:209], v[118:121]
	v_mfma_f32_16x16x32_bf16 v[114:117], v[162:165], v[206:209], v[114:117]
	v_mfma_f32_16x16x32_bf16 v[126:129], v[154:157], v[218:221], v[126:129]
	v_mfma_f32_16x16x32_bf16 v[122:125], v[162:165], v[218:221], v[122:125]
	v_mfma_f32_16x16x32_bf16 v[92:95], v[154:157], v[226:229], v[92:95]
	v_mfma_f32_16x16x32_bf16 v[88:91], v[162:165], v[226:229], v[88:91]
	v_mfma_f32_16x16x32_bf16 v[110:113], v[158:161], v[202:205], v[110:113]
	v_mfma_f32_16x16x32_bf16 v[106:109], v[166:169], v[202:205], v[106:109]
	v_mfma_f32_16x16x32_bf16 v[118:121], v[158:161], v[214:217], v[118:121]
	v_mfma_f32_16x16x32_bf16 v[114:117], v[166:169], v[214:217], v[114:117]
	v_mfma_f32_16x16x32_bf16 v[126:129], v[158:161], v[222:225], v[126:129]
	v_mfma_f32_16x16x32_bf16 v[122:125], v[166:169], v[222:225], v[122:125]
	v_mfma_f32_16x16x32_bf16 v[92:95], v[158:161], v[230:233], v[92:95]
	v_mfma_f32_16x16x32_bf16 v[88:91], v[166:169], v[230:233], v[88:91]
	s_setprio 0
	s_setprio 1
	v_mfma_f32_16x16x32_bf16 v[4:7], v[174:177], v[190:193], v[4:7]
	v_mfma_f32_16x16x32_bf16 v[0:3], v[182:185], v[190:193], v[0:3]
	v_mfma_f32_16x16x32_bf16 v[12:15], v[174:177], v[206:209], v[12:15]
	v_mfma_f32_16x16x32_bf16 v[8:11], v[182:185], v[206:209], v[8:11]
	v_mfma_f32_16x16x32_bf16 v[24:27], v[174:177], v[218:221], v[24:27]
	v_mfma_f32_16x16x32_bf16 v[20:23], v[182:185], v[218:221], v[20:23]
	v_mfma_f32_16x16x32_bf16 v[40:43], v[174:177], v[226:229], v[40:43]
	v_mfma_f32_16x16x32_bf16 v[32:35], v[182:185], v[226:229], v[32:35]
	v_mfma_f32_16x16x32_bf16 v[4:7], v[178:181], v[202:205], v[4:7]
	v_mfma_f32_16x16x32_bf16 v[0:3], v[186:189], v[202:205], v[0:3]
	v_mfma_f32_16x16x32_bf16 v[12:15], v[178:181], v[214:217], v[12:15]
	v_mfma_f32_16x16x32_bf16 v[8:11], v[186:189], v[214:217], v[8:11]
	v_mfma_f32_16x16x32_bf16 v[24:27], v[178:181], v[222:225], v[24:27]
	v_mfma_f32_16x16x32_bf16 v[20:23], v[186:189], v[222:225], v[20:23]
	v_mfma_f32_16x16x32_bf16 v[40:43], v[178:181], v[230:233], v[40:43]
	v_mfma_f32_16x16x32_bf16 v[32:35], v[186:189], v[230:233], v[32:35]
	s_setprio 0
	s_barrier
	s_add_i32 s6, s63, s5
	s_mov_b32 m0, s6
	ds_read_b128 v[190:193], v145 offset:16384
	ds_read_b128 v[202:205], v145 offset:17408
	ds_read_b128 v[206:209], v145 offset:18432
	ds_read_b128 v[214:217], v145 offset:19456
	ds_read_b128 v[218:221], v145 offset:20480
	ds_read_b128 v[222:225], v145 offset:21504
	ds_read_b128 v[226:229], v145 offset:22528
	ds_read_b128 v[230:233], v145 offset:23552
	global_load_lds_dwordx4 v96, s[48:49]
	s_add_i32 m0, s6, 0x2000
	s_add_u32 s72, s48, 0x80000
	s_addc_u32 s73, s49, 0
	s_add_i32 s3, s3, s5
	global_load_lds_dwordx4 v130, s[48:49]
	s_mov_b32 m0, s3
	s_nop 0
	global_load_lds_dwordx4 v96, s[72:73]
	s_add_i32 m0, s3, 0x2000
	s_nop 0
	global_load_lds_dwordx4 v130, s[72:73]
	s_mov_b32 m0, s17
	s_nop 0
	global_load_lds_dwordx4 v134, s[50:51]
	s_mov_b32 m0, s18
	s_nop 0
	global_load_lds_dwordx4 v132, s[50:51]
	s_waitcnt vmcnt(8)
	s_waitcnt lgkmcnt(0)
	s_barrier
	s_setprio 1
	s_waitcnt lgkmcnt(0)
	v_mfma_f32_16x16x32_bf16 v[102:105], v[154:157], v[190:193], v[102:105]
	v_mfma_f32_16x16x32_bf16 v[98:101], v[162:165], v[190:193], v[98:101]
	v_mfma_f32_16x16x32_bf16 v[84:87], v[154:157], v[206:209], v[84:87]
	v_mfma_f32_16x16x32_bf16 v[80:83], v[162:165], v[206:209], v[80:83]
	v_mfma_f32_16x16x32_bf16 v[68:71], v[154:157], v[218:221], v[68:71]
	v_mfma_f32_16x16x32_bf16 v[64:67], v[162:165], v[218:221], v[64:67]
	v_mfma_f32_16x16x32_bf16 v[44:47], v[154:157], v[226:229], v[44:47]
	v_mfma_f32_16x16x32_bf16 v[36:39], v[162:165], v[226:229], v[36:39]
	v_mfma_f32_16x16x32_bf16 v[102:105], v[158:161], v[202:205], v[102:105]
	v_mfma_f32_16x16x32_bf16 v[98:101], v[166:169], v[202:205], v[98:101]
	v_mfma_f32_16x16x32_bf16 v[84:87], v[158:161], v[214:217], v[84:87]
	v_mfma_f32_16x16x32_bf16 v[80:83], v[166:169], v[214:217], v[80:83]
	v_mfma_f32_16x16x32_bf16 v[68:71], v[158:161], v[222:225], v[68:71]
	v_mfma_f32_16x16x32_bf16 v[64:67], v[166:169], v[222:225], v[64:67]
	v_mfma_f32_16x16x32_bf16 v[44:47], v[158:161], v[230:233], v[44:47]
	v_mfma_f32_16x16x32_bf16 v[36:39], v[166:169], v[230:233], v[36:39]
	s_setprio 0
	s_setprio 1
	v_mfma_f32_16x16x32_bf16 v[60:63], v[174:177], v[190:193], v[60:63]
	v_mfma_f32_16x16x32_bf16 v[56:59], v[182:185], v[190:193], v[56:59]
	v_mfma_f32_16x16x32_bf16 v[76:79], v[174:177], v[206:209], v[76:79]
	v_mfma_f32_16x16x32_bf16 v[72:75], v[182:185], v[206:209], v[72:75]
	v_mfma_f32_16x16x32_bf16 v[52:55], v[174:177], v[218:221], v[52:55]
	v_mfma_f32_16x16x32_bf16 v[48:51], v[182:185], v[218:221], v[48:51]
	v_mfma_f32_16x16x32_bf16 v[28:31], v[174:177], v[226:229], v[28:31]
	v_mfma_f32_16x16x32_bf16 v[16:19], v[182:185], v[226:229], v[16:19]
	v_mfma_f32_16x16x32_bf16 v[60:63], v[178:181], v[202:205], v[60:63]
	v_mfma_f32_16x16x32_bf16 v[56:59], v[186:189], v[202:205], v[56:59]
	v_mfma_f32_16x16x32_bf16 v[76:79], v[178:181], v[214:217], v[76:79]
	v_mfma_f32_16x16x32_bf16 v[72:75], v[186:189], v[214:217], v[72:75]
	v_mfma_f32_16x16x32_bf16 v[52:55], v[178:181], v[222:225], v[52:55]
	v_mfma_f32_16x16x32_bf16 v[48:51], v[186:189], v[222:225], v[48:51]
	v_mfma_f32_16x16x32_bf16 v[28:31], v[178:181], v[230:233], v[28:31]
	v_mfma_f32_16x16x32_bf16 v[16:19], v[186:189], v[230:233], v[16:19]
	s_setprio 0
	s_barrier
	s_add_i32 s3, 0, 0x18000
	v_add_u32_e32 v149, s3, v144
	s_add_i32 s6, 0, 0x1c000
	ds_read_b128 v[154:157], v149
	ds_read_b128 v[158:161], v149 offset:1024
	ds_read_b128 v[162:165], v149 offset:2048
	ds_read_b128 v[166:169], v149 offset:3072
	v_add_u32_e32 v149, s6, v144
	ds_read_b128 v[174:177], v149
	ds_read_b128 v[178:181], v149 offset:1024
	ds_read_b128 v[182:185], v149 offset:2048
	ds_read_b128 v[186:189], v149 offset:3072
	s_add_u32 s50, s50, 0x80000
	s_addc_u32 s51, s51, 0
	s_mov_b32 m0, s19
	ds_read_b128 v[190:193], v145 offset:32768
	ds_read_b128 v[202:205], v145 offset:33792
	ds_read_b128 v[206:209], v145 offset:34816
	ds_read_b128 v[214:217], v145 offset:35840
	ds_read_b128 v[218:221], v145 offset:36864
	ds_read_b128 v[222:225], v145 offset:37888
	ds_read_b128 v[226:229], v145 offset:38912
	ds_read_b128 v[230:233], v145 offset:39936
	global_load_lds_dwordx4 v134, s[50:51]
	s_mov_b32 m0, s20
	s_nop 0
	global_load_lds_dwordx4 v132, s[50:51]
	s_waitcnt vmcnt(8)
	s_waitcnt lgkmcnt(0)
	s_barrier
	s_setprio 1
	s_waitcnt lgkmcnt(0)
	v_mfma_f32_16x16x32_bf16 v[110:113], v[154:157], v[190:193], v[110:113]
	v_mfma_f32_16x16x32_bf16 v[106:109], v[162:165], v[190:193], v[106:109]
	v_mfma_f32_16x16x32_bf16 v[118:121], v[154:157], v[206:209], v[118:121]
	v_mfma_f32_16x16x32_bf16 v[114:117], v[162:165], v[206:209], v[114:117]
	v_mfma_f32_16x16x32_bf16 v[126:129], v[154:157], v[218:221], v[126:129]
	v_mfma_f32_16x16x32_bf16 v[122:125], v[162:165], v[218:221], v[122:125]
	v_mfma_f32_16x16x32_bf16 v[92:95], v[154:157], v[226:229], v[92:95]
	v_mfma_f32_16x16x32_bf16 v[88:91], v[162:165], v[226:229], v[88:91]
	v_mfma_f32_16x16x32_bf16 v[110:113], v[158:161], v[202:205], v[110:113]
	v_mfma_f32_16x16x32_bf16 v[106:109], v[166:169], v[202:205], v[106:109]
	v_mfma_f32_16x16x32_bf16 v[118:121], v[158:161], v[214:217], v[118:121]
	v_mfma_f32_16x16x32_bf16 v[114:117], v[166:169], v[214:217], v[114:117]
	v_mfma_f32_16x16x32_bf16 v[126:129], v[158:161], v[222:225], v[126:129]
	v_mfma_f32_16x16x32_bf16 v[122:125], v[166:169], v[222:225], v[122:125]
	v_mfma_f32_16x16x32_bf16 v[92:95], v[158:161], v[230:233], v[92:95]
	v_mfma_f32_16x16x32_bf16 v[88:91], v[166:169], v[230:233], v[88:91]
	s_setprio 0
	s_setprio 1
	v_mfma_f32_16x16x32_bf16 v[4:7], v[174:177], v[190:193], v[4:7]
	v_mfma_f32_16x16x32_bf16 v[0:3], v[182:185], v[190:193], v[0:3]
	v_mfma_f32_16x16x32_bf16 v[12:15], v[174:177], v[206:209], v[12:15]
	v_mfma_f32_16x16x32_bf16 v[8:11], v[182:185], v[206:209], v[8:11]
	v_mfma_f32_16x16x32_bf16 v[24:27], v[174:177], v[218:221], v[24:27]
	v_mfma_f32_16x16x32_bf16 v[20:23], v[182:185], v[218:221], v[20:23]
	v_mfma_f32_16x16x32_bf16 v[40:43], v[174:177], v[226:229], v[40:43]
	v_mfma_f32_16x16x32_bf16 v[32:35], v[182:185], v[226:229], v[32:35]
	v_mfma_f32_16x16x32_bf16 v[4:7], v[178:181], v[202:205], v[4:7]
	v_mfma_f32_16x16x32_bf16 v[0:3], v[186:189], v[202:205], v[0:3]
	v_mfma_f32_16x16x32_bf16 v[12:15], v[178:181], v[214:217], v[12:15]
	v_mfma_f32_16x16x32_bf16 v[8:11], v[186:189], v[214:217], v[8:11]
	v_mfma_f32_16x16x32_bf16 v[24:27], v[178:181], v[222:225], v[24:27]
	v_mfma_f32_16x16x32_bf16 v[20:23], v[186:189], v[222:225], v[20:23]
	v_mfma_f32_16x16x32_bf16 v[40:43], v[178:181], v[230:233], v[40:43]
	v_mfma_f32_16x16x32_bf16 v[32:35], v[186:189], v[230:233], v[32:35]
	s_setprio 0
	s_barrier
	s_add_i32 s3, s3, s5
	s_mov_b32 m0, s3
	ds_read_b128 v[190:193], v145 offset:49152
	ds_read_b128 v[202:205], v145 offset:50176
	ds_read_b128 v[206:209], v145 offset:51200
	ds_read_b128 v[214:217], v145 offset:52224
	ds_read_b128 v[218:221], v145 offset:53248
	ds_read_b128 v[222:225], v145 offset:54272
	ds_read_b128 v[226:229], v145 offset:55296
	ds_read_b128 v[230:233], v145 offset:56320
	s_add_u32 s100, s48, 0x80
	s_addc_u32 s101, s49, 0
	global_load_lds_dwordx4 v96, s[100:101]
	s_add_i32 m0, s3, 0x2000
	s_add_u32 s48, s48, 0x80080
	s_addc_u32 s49, s49, 0
	s_add_i32 s3, s6, s5
	global_load_lds_dwordx4 v130, s[100:101]
	s_mov_b32 m0, s3
	s_nop 0
	global_load_lds_dwordx4 v96, s[48:49]
	s_add_i32 m0, s3, 0x2000
	s_nop 0
	global_load_lds_dwordx4 v130, s[48:49]
	s_mov_b32 m0, s37
	s_nop 0
	s_sub_u32 s100, s50, 0x7ff80
	s_subb_u32 s101, s51, 0
	global_load_lds_dwordx4 v134, s[100:101]
	s_mov_b32 m0, s56
	s_nop 0
	global_load_lds_dwordx4 v132, s[100:101]
	s_waitcnt vmcnt(8)
	s_waitcnt lgkmcnt(0)
	s_barrier
	s_setprio 1
	s_waitcnt lgkmcnt(0)
	v_mfma_f32_16x16x32_bf16 v[102:105], v[154:157], v[190:193], v[102:105]
	v_mfma_f32_16x16x32_bf16 v[98:101], v[162:165], v[190:193], v[98:101]
	v_mfma_f32_16x16x32_bf16 v[84:87], v[154:157], v[206:209], v[84:87]
	v_mfma_f32_16x16x32_bf16 v[80:83], v[162:165], v[206:209], v[80:83]
	v_mfma_f32_16x16x32_bf16 v[68:71], v[154:157], v[218:221], v[68:71]
	v_mfma_f32_16x16x32_bf16 v[64:67], v[162:165], v[218:221], v[64:67]
	v_mfma_f32_16x16x32_bf16 v[44:47], v[154:157], v[226:229], v[44:47]
	v_mfma_f32_16x16x32_bf16 v[36:39], v[162:165], v[226:229], v[36:39]
	v_mfma_f32_16x16x32_bf16 v[102:105], v[158:161], v[202:205], v[102:105]
	v_mfma_f32_16x16x32_bf16 v[98:101], v[166:169], v[202:205], v[98:101]
	v_mfma_f32_16x16x32_bf16 v[84:87], v[158:161], v[214:217], v[84:87]
	v_mfma_f32_16x16x32_bf16 v[80:83], v[166:169], v[214:217], v[80:83]
	v_mfma_f32_16x16x32_bf16 v[68:71], v[158:161], v[222:225], v[68:71]
	v_mfma_f32_16x16x32_bf16 v[64:67], v[166:169], v[222:225], v[64:67]
	v_mfma_f32_16x16x32_bf16 v[44:47], v[158:161], v[230:233], v[44:47]
	v_mfma_f32_16x16x32_bf16 v[36:39], v[166:169], v[230:233], v[36:39]
	s_setprio 0
	s_setprio 1
	v_mfma_f32_16x16x32_bf16 v[60:63], v[174:177], v[190:193], v[60:63]
	v_mfma_f32_16x16x32_bf16 v[56:59], v[182:185], v[190:193], v[56:59]
	v_mfma_f32_16x16x32_bf16 v[76:79], v[174:177], v[206:209], v[76:79]
	v_mfma_f32_16x16x32_bf16 v[72:75], v[182:185], v[206:209], v[72:75]
	v_mfma_f32_16x16x32_bf16 v[52:55], v[174:177], v[218:221], v[52:55]
	v_mfma_f32_16x16x32_bf16 v[48:51], v[182:185], v[218:221], v[48:51]
	v_mfma_f32_16x16x32_bf16 v[28:31], v[174:177], v[226:229], v[28:31]
	v_mfma_f32_16x16x32_bf16 v[16:19], v[182:185], v[226:229], v[16:19]
	v_mfma_f32_16x16x32_bf16 v[60:63], v[178:181], v[202:205], v[60:63]
	v_mfma_f32_16x16x32_bf16 v[56:59], v[186:189], v[202:205], v[56:59]
	v_mfma_f32_16x16x32_bf16 v[76:79], v[178:181], v[214:217], v[76:79]
	v_mfma_f32_16x16x32_bf16 v[72:75], v[186:189], v[214:217], v[72:75]
	v_mfma_f32_16x16x32_bf16 v[52:55], v[178:181], v[222:225], v[52:55]
	v_mfma_f32_16x16x32_bf16 v[48:51], v[186:189], v[222:225], v[48:51]
	v_mfma_f32_16x16x32_bf16 v[28:31], v[178:181], v[230:233], v[28:31]
	v_mfma_f32_16x16x32_bf16 v[16:19], v[186:189], v[230:233], v[16:19]
	s_setprio 0
	s_barrier
	s_add_i32 s2, s2, 2
	s_add_u32 s46, s46, 0x100
	s_addc_u32 s47, s47, 0
	s_cmp_gt_u32 s2, 29
	s_cbranch_scc0 .LBB0_993
	s_nop 0
	s_nop 0
	s_nop 0
	s_nop 0
	s_nop 0
	s_and_b64 vcc, exec, s[12:13]
	s_cbranch_vccz .LBB0_996
	s_barrier

.LBB0_1333:
	s_add_u32 s38, s42, 0x100
	s_addc_u32 s39, s43, 0
	s_add_i32 s13, 0, 0x10000
	s_cmp_eq_u32 s6, 4
	s_cselect_b32 s47, s25, s39
	s_cselect_b32 s46, s24, s38
	s_cselect_b32 s45, s35, s3
	s_cselect_b32 s44, s34, s2
	s_add_i32 s23, 0, 0x14000
	v_add_u32_e32 v152, s13, v136
	v_add_u32_e32 v168, s23, v136
	ds_read_b128 v[140:143], v152
	ds_read_b128 v[144:147], v152 offset:1024
	ds_read_b128 v[148:151], v152 offset:2048
	ds_read_b128 v[152:155], v152 offset:3072
	ds_read_b128 v[156:159], v168
	ds_read_b128 v[160:163], v168 offset:1024
	ds_read_b128 v[164:167], v168 offset:2048
	ds_read_b128 v[168:171], v168 offset:3072
	s_add_i32 m0, s5, 0xc000
	ds_read_b128 v[172:175], v139
	ds_read_b128 v[176:179], v139 offset:1024
	ds_read_b128 v[180:183], v139 offset:2048
	ds_read_b128 v[184:187], v139 offset:3072
	ds_read_b128 v[188:191], v139 offset:4096
	ds_read_b128 v[192:195], v139 offset:5120
	ds_read_b128 v[202:205], v139 offset:6144
	ds_read_b128 v[206:209], v139 offset:7168
	global_load_lds_dwordx4 v132, s[42:43]
	s_add_i32 m0, s5, 0xe000
	s_nop 0
	global_load_lds_dwordx4 v134, s[42:43]
	s_waitcnt vmcnt(8)
	s_waitcnt lgkmcnt(0)
	s_barrier
	s_setprio 1
	s_waitcnt lgkmcnt(0)
	v_mfma_f32_16x16x32_bf16 v[126:129], v[140:143], v[172:175], v[126:129]
	v_mfma_f32_16x16x32_bf16 v[122:125], v[148:151], v[172:175], v[122:125]
	v_mfma_f32_16x16x32_bf16 v[118:121], v[140:143], v[180:183], v[118:121]
	v_mfma_f32_16x16x32_bf16 v[114:117], v[148:151], v[180:183], v[114:117]
	v_mfma_f32_16x16x32_bf16 v[106:109], v[140:143], v[188:191], v[106:109]
	v_mfma_f32_16x16x32_bf16 v[98:101], v[148:151], v[188:191], v[98:101]
	v_mfma_f32_16x16x32_bf16 v[88:91], v[140:143], v[202:205], v[88:91]
	v_mfma_f32_16x16x32_bf16 v[80:83], v[148:151], v[202:205], v[80:83]
	v_mfma_f32_16x16x32_bf16 v[126:129], v[144:147], v[176:179], v[126:129]
	v_mfma_f32_16x16x32_bf16 v[122:125], v[152:155], v[176:179], v[122:125]
	v_mfma_f32_16x16x32_bf16 v[118:121], v[144:147], v[184:187], v[118:121]
	v_mfma_f32_16x16x32_bf16 v[114:117], v[152:155], v[184:187], v[114:117]
	v_mfma_f32_16x16x32_bf16 v[106:109], v[144:147], v[192:195], v[106:109]
	v_mfma_f32_16x16x32_bf16 v[98:101], v[152:155], v[192:195], v[98:101]
	v_mfma_f32_16x16x32_bf16 v[88:91], v[144:147], v[206:209], v[88:91]
	v_mfma_f32_16x16x32_bf16 v[80:83], v[152:155], v[206:209], v[80:83]
	s_setprio 0
	s_setprio 1
	v_mfma_f32_16x16x32_bf16 v[110:113], v[156:159], v[172:175], v[110:113]
	v_mfma_f32_16x16x32_bf16 v[102:105], v[164:167], v[172:175], v[102:105]
	v_mfma_f32_16x16x32_bf16 v[92:95], v[156:159], v[180:183], v[92:95]
	v_mfma_f32_16x16x32_bf16 v[84:87], v[164:167], v[180:183], v[84:87]
	v_mfma_f32_16x16x32_bf16 v[76:79], v[156:159], v[188:191], v[76:79]
	v_mfma_f32_16x16x32_bf16 v[72:75], v[164:167], v[188:191], v[72:75]
	v_mfma_f32_16x16x32_bf16 v[68:71], v[156:159], v[202:205], v[68:71]
	v_mfma_f32_16x16x32_bf16 v[64:67], v[164:167], v[202:205], v[64:67]
	v_mfma_f32_16x16x32_bf16 v[110:113], v[160:163], v[176:179], v[110:113]
	v_mfma_f32_16x16x32_bf16 v[102:105], v[168:171], v[176:179], v[102:105]
	v_mfma_f32_16x16x32_bf16 v[92:95], v[160:163], v[184:187], v[92:95]
	v_mfma_f32_16x16x32_bf16 v[84:87], v[168:171], v[184:187], v[84:87]
	v_mfma_f32_16x16x32_bf16 v[76:79], v[160:163], v[192:195], v[76:79]
	v_mfma_f32_16x16x32_bf16 v[72:75], v[168:171], v[192:195], v[72:75]
	v_mfma_f32_16x16x32_bf16 v[68:71], v[160:163], v[206:209], v[68:71]
	v_mfma_f32_16x16x32_bf16 v[64:67], v[168:171], v[206:209], v[64:67]
	s_setprio 0
	s_barrier
	s_add_i32 s13, s13, s4
	s_mov_b32 m0, s13
	ds_read_b128 v[172:175], v139 offset:16384
	ds_read_b128 v[176:179], v139 offset:17408
	ds_read_b128 v[180:183], v139 offset:18432
	ds_read_b128 v[184:187], v139 offset:19456
	ds_read_b128 v[188:191], v139 offset:20480
	ds_read_b128 v[192:195], v139 offset:21504
	ds_read_b128 v[202:205], v139 offset:22528
	ds_read_b128 v[206:209], v139 offset:23552
	global_load_lds_dwordx4 v96, s[44:45]
	s_add_i32 m0, s13, 0x2000
	s_add_u32 s42, s44, 0x160000
	s_addc_u32 s43, s45, 0
	s_add_i32 s13, s23, s4
	global_load_lds_dwordx4 v130, s[44:45]
	s_mov_b32 m0, s13
	s_nop 0
	global_load_lds_dwordx4 v96, s[42:43]
	s_add_i32 m0, s13, 0x2000
	s_nop 0
	global_load_lds_dwordx4 v130, s[42:43]
	s_mov_b32 m0, s5
	s_nop 0
	global_load_lds_dwordx4 v96, s[46:47]
	s_mov_b32 m0, s17
	s_nop 0
	global_load_lds_dwordx4 v130, s[46:47]
	s_waitcnt vmcnt(8)
	s_waitcnt lgkmcnt(0)
	s_barrier
	s_setprio 1
	s_waitcnt lgkmcnt(0)
	v_mfma_f32_16x16x32_bf16 v[60:63], v[140:143], v[172:175], v[60:63]
	v_mfma_f32_16x16x32_bf16 v[56:59], v[148:151], v[172:175], v[56:59]
	v_mfma_f32_16x16x32_bf16 v[52:55], v[140:143], v[180:183], v[52:55]
	v_mfma_f32_16x16x32_bf16 v[48:51], v[148:151], v[180:183], v[48:51]
	v_mfma_f32_16x16x32_bf16 v[36:39], v[140:143], v[188:191], v[36:39]
	v_mfma_f32_16x16x32_bf16 v[32:35], v[148:151], v[188:191], v[32:35]
	v_mfma_f32_16x16x32_bf16 v[20:23], v[140:143], v[202:205], v[20:23]
	v_mfma_f32_16x16x32_bf16 v[16:19], v[148:151], v[202:205], v[16:19]
	v_mfma_f32_16x16x32_bf16 v[60:63], v[144:147], v[176:179], v[60:63]
	v_mfma_f32_16x16x32_bf16 v[56:59], v[152:155], v[176:179], v[56:59]
	v_mfma_f32_16x16x32_bf16 v[52:55], v[144:147], v[184:187], v[52:55]
	v_mfma_f32_16x16x32_bf16 v[48:51], v[152:155], v[184:187], v[48:51]
	v_mfma_f32_16x16x32_bf16 v[36:39], v[144:147], v[192:195], v[36:39]
	v_mfma_f32_16x16x32_bf16 v[32:35], v[152:155], v[192:195], v[32:35]
	v_mfma_f32_16x16x32_bf16 v[20:23], v[144:147], v[206:209], v[20:23]
	v_mfma_f32_16x16x32_bf16 v[16:19], v[152:155], v[206:209], v[16:19]
	s_setprio 0
	s_setprio 1
	v_mfma_f32_16x16x32_bf16 v[44:47], v[156:159], v[172:175], v[44:47]
	v_mfma_f32_16x16x32_bf16 v[40:43], v[164:167], v[172:175], v[40:43]
	v_mfma_f32_16x16x32_bf16 v[28:31], v[156:159], v[180:183], v[28:31]
	v_mfma_f32_16x16x32_bf16 v[24:27], v[164:167], v[180:183], v[24:27]
	v_mfma_f32_16x16x32_bf16 v[12:15], v[156:159], v[188:191], v[12:15]
	v_mfma_f32_16x16x32_bf16 v[8:11], v[164:167], v[188:191], v[8:11]
	v_mfma_f32_16x16x32_bf16 v[4:7], v[156:159], v[202:205], v[4:7]
	v_mfma_f32_16x16x32_bf16 v[0:3], v[164:167], v[202:205], v[0:3]
	v_mfma_f32_16x16x32_bf16 v[44:47], v[160:163], v[176:179], v[44:47]
	v_mfma_f32_16x16x32_bf16 v[40:43], v[168:171], v[176:179], v[40:43]
	v_mfma_f32_16x16x32_bf16 v[28:31], v[160:163], v[184:187], v[28:31]
	v_mfma_f32_16x16x32_bf16 v[24:27], v[168:171], v[184:187], v[24:27]
	v_mfma_f32_16x16x32_bf16 v[12:15], v[160:163], v[192:195], v[12:15]
	v_mfma_f32_16x16x32_bf16 v[8:11], v[168:171], v[192:195], v[8:11]
	v_mfma_f32_16x16x32_bf16 v[4:7], v[160:163], v[206:209], v[4:7]
	v_mfma_f32_16x16x32_bf16 v[0:3], v[168:171], v[206:209], v[0:3]
	s_setprio 0
	s_barrier
	s_add_i32 s13, 0, 0x18000
	s_add_i32 s23, 0, 0x1c000
	v_add_u32_e32 v152, s13, v136
	v_add_u32_e32 v168, s23, v136
	ds_read_b128 v[140:143], v152
	ds_read_b128 v[144:147], v152 offset:1024
	ds_read_b128 v[148:151], v152 offset:2048
	ds_read_b128 v[152:155], v152 offset:3072
	ds_read_b128 v[156:159], v168
	ds_read_b128 v[160:163], v168 offset:1024
	ds_read_b128 v[164:167], v168 offset:2048
	ds_read_b128 v[168:171], v168 offset:3072
	s_add_u32 s42, s46, 0x160000
	s_addc_u32 s43, s47, 0
	s_mov_b32 m0, s18
	ds_read_b128 v[172:175], v139 offset:32768
	ds_read_b128 v[176:179], v139 offset:33792
	ds_read_b128 v[180:183], v139 offset:34816
	ds_read_b128 v[184:187], v139 offset:35840
	ds_read_b128 v[188:191], v139 offset:36864
	ds_read_b128 v[192:195], v139 offset:37888
	ds_read_b128 v[202:205], v139 offset:38912
	ds_read_b128 v[206:209], v139 offset:39936
	global_load_lds_dwordx4 v96, s[42:43]
	s_mov_b32 m0, s19
	s_nop 0
	global_load_lds_dwordx4 v130, s[42:43]
	s_waitcnt vmcnt(8)
	s_waitcnt lgkmcnt(0)
	s_barrier
	s_setprio 1
	s_waitcnt lgkmcnt(0)
	v_mfma_f32_16x16x32_bf16 v[126:129], v[140:143], v[172:175], v[126:129]
	v_mfma_f32_16x16x32_bf16 v[122:125], v[148:151], v[172:175], v[122:125]
	v_mfma_f32_16x16x32_bf16 v[118:121], v[140:143], v[180:183], v[118:121]
	v_mfma_f32_16x16x32_bf16 v[114:117], v[148:151], v[180:183], v[114:117]
	v_mfma_f32_16x16x32_bf16 v[106:109], v[140:143], v[188:191], v[106:109]
	v_mfma_f32_16x16x32_bf16 v[98:101], v[148:151], v[188:191], v[98:101]
	v_mfma_f32_16x16x32_bf16 v[88:91], v[140:143], v[202:205], v[88:91]
	v_mfma_f32_16x16x32_bf16 v[80:83], v[148:151], v[202:205], v[80:83]
	v_mfma_f32_16x16x32_bf16 v[126:129], v[144:147], v[176:179], v[126:129]
	v_mfma_f32_16x16x32_bf16 v[122:125], v[152:155], v[176:179], v[122:125]
	v_mfma_f32_16x16x32_bf16 v[118:121], v[144:147], v[184:187], v[118:121]
	v_mfma_f32_16x16x32_bf16 v[114:117], v[152:155], v[184:187], v[114:117]
	v_mfma_f32_16x16x32_bf16 v[106:109], v[144:147], v[192:195], v[106:109]
	v_mfma_f32_16x16x32_bf16 v[98:101], v[152:155], v[192:195], v[98:101]
	v_mfma_f32_16x16x32_bf16 v[88:91], v[144:147], v[206:209], v[88:91]
	v_mfma_f32_16x16x32_bf16 v[80:83], v[152:155], v[206:209], v[80:83]
	s_setprio 0
	s_setprio 1
	v_mfma_f32_16x16x32_bf16 v[110:113], v[156:159], v[172:175], v[110:113]
	v_mfma_f32_16x16x32_bf16 v[102:105], v[164:167], v[172:175], v[102:105]
	v_mfma_f32_16x16x32_bf16 v[92:95], v[156:159], v[180:183], v[92:95]
	v_mfma_f32_16x16x32_bf16 v[84:87], v[164:167], v[180:183], v[84:87]
	v_mfma_f32_16x16x32_bf16 v[76:79], v[156:159], v[188:191], v[76:79]
	v_mfma_f32_16x16x32_bf16 v[72:75], v[164:167], v[188:191], v[72:75]
	v_mfma_f32_16x16x32_bf16 v[68:71], v[156:159], v[202:205], v[68:71]
	v_mfma_f32_16x16x32_bf16 v[64:67], v[164:167], v[202:205], v[64:67]
	v_mfma_f32_16x16x32_bf16 v[110:113], v[160:163], v[176:179], v[110:113]
	v_mfma_f32_16x16x32_bf16 v[102:105], v[168:171], v[176:179], v[102:105]
	v_mfma_f32_16x16x32_bf16 v[92:95], v[160:163], v[184:187], v[92:95]
	v_mfma_f32_16x16x32_bf16 v[84:87], v[168:171], v[184:187], v[84:87]
	v_mfma_f32_16x16x32_bf16 v[76:79], v[160:163], v[192:195], v[76:79]
	v_mfma_f32_16x16x32_bf16 v[72:75], v[168:171], v[192:195], v[72:75]
	v_mfma_f32_16x16x32_bf16 v[68:71], v[160:163], v[206:209], v[68:71]
	v_mfma_f32_16x16x32_bf16 v[64:67], v[168:171], v[206:209], v[64:67]
	s_setprio 0
	s_barrier
	s_add_i32 s13, s13, s4
	s_mov_b32 m0, s13
	ds_read_b128 v[172:175], v139 offset:49152
	ds_read_b128 v[176:179], v139 offset:50176
	ds_read_b128 v[180:183], v139 offset:51200
	ds_read_b128 v[184:187], v139 offset:52224
	ds_read_b128 v[188:191], v139 offset:53248
	ds_read_b128 v[192:195], v139 offset:54272
	ds_read_b128 v[202:205], v139 offset:55296
	ds_read_b128 v[206:209], v139 offset:56320
	s_add_u32 s100, s44, 0x80
	s_addc_u32 s101, s45, 0
	global_load_lds_dwordx4 v96, s[100:101]
	s_add_i32 m0, s13, 0x2000
	s_add_u32 s42, s44, 0x160080
	s_addc_u32 s43, s45, 0
	s_add_i32 s13, s23, s4
	global_load_lds_dwordx4 v130, s[100:101]
	s_mov_b32 m0, s13
	s_nop 0
	global_load_lds_dwordx4 v96, s[42:43]
	s_add_i32 m0, s13, 0x2000
	s_nop 0
	global_load_lds_dwordx4 v130, s[42:43]
	s_mov_b32 m0, s37
	s_nop 0
	s_add_u32 s100, s46, 0x80
	s_addc_u32 s101, s47, 0
	global_load_lds_dwordx4 v96, s[100:101]
	s_mov_b32 m0, s40
	s_nop 0
	global_load_lds_dwordx4 v130, s[100:101]
	s_waitcnt vmcnt(8)
	s_waitcnt lgkmcnt(0)
	s_barrier
	s_setprio 1
	s_waitcnt lgkmcnt(0)
	v_mfma_f32_16x16x32_bf16 v[60:63], v[140:143], v[172:175], v[60:63]
	v_mfma_f32_16x16x32_bf16 v[56:59], v[148:151], v[172:175], v[56:59]
	v_mfma_f32_16x16x32_bf16 v[52:55], v[140:143], v[180:183], v[52:55]
	v_mfma_f32_16x16x32_bf16 v[48:51], v[148:151], v[180:183], v[48:51]
	v_mfma_f32_16x16x32_bf16 v[36:39], v[140:143], v[188:191], v[36:39]
	v_mfma_f32_16x16x32_bf16 v[32:35], v[148:151], v[188:191], v[32:35]
	v_mfma_f32_16x16x32_bf16 v[20:23], v[140:143], v[202:205], v[20:23]
	v_mfma_f32_16x16x32_bf16 v[16:19], v[148:151], v[202:205], v[16:19]
	v_mfma_f32_16x16x32_bf16 v[60:63], v[144:147], v[176:179], v[60:63]
	v_mfma_f32_16x16x32_bf16 v[56:59], v[152:155], v[176:179], v[56:59]
	v_mfma_f32_16x16x32_bf16 v[52:55], v[144:147], v[184:187], v[52:55]
	v_mfma_f32_16x16x32_bf16 v[48:51], v[152:155], v[184:187], v[48:51]
	v_mfma_f32_16x16x32_bf16 v[36:39], v[144:147], v[192:195], v[36:39]
	v_mfma_f32_16x16x32_bf16 v[32:35], v[152:155], v[192:195], v[32:35]
	v_mfma_f32_16x16x32_bf16 v[20:23], v[144:147], v[206:209], v[20:23]
	v_mfma_f32_16x16x32_bf16 v[16:19], v[152:155], v[206:209], v[16:19]
	s_setprio 0
	s_setprio 1
	v_mfma_f32_16x16x32_bf16 v[44:47], v[156:159], v[172:175], v[44:47]
	v_mfma_f32_16x16x32_bf16 v[40:43], v[164:167], v[172:175], v[40:43]
	v_mfma_f32_16x16x32_bf16 v[28:31], v[156:159], v[180:183], v[28:31]
	v_mfma_f32_16x16x32_bf16 v[24:27], v[164:167], v[180:183], v[24:27]
	v_mfma_f32_16x16x32_bf16 v[12:15], v[156:159], v[188:191], v[12:15]
	v_mfma_f32_16x16x32_bf16 v[8:11], v[164:167], v[188:191], v[8:11]
	v_mfma_f32_16x16x32_bf16 v[4:7], v[156:159], v[202:205], v[4:7]
	v_mfma_f32_16x16x32_bf16 v[0:3], v[164:167], v[202:205], v[0:3]
	v_mfma_f32_16x16x32_bf16 v[44:47], v[160:163], v[176:179], v[44:47]
	v_mfma_f32_16x16x32_bf16 v[40:43], v[168:171], v[176:179], v[40:43]
	v_mfma_f32_16x16x32_bf16 v[28:31], v[160:163], v[184:187], v[28:31]
	v_mfma_f32_16x16x32_bf16 v[24:27], v[168:171], v[184:187], v[24:27]
	v_mfma_f32_16x16x32_bf16 v[12:15], v[160:163], v[192:195], v[12:15]
	v_mfma_f32_16x16x32_bf16 v[8:11], v[168:171], v[192:195], v[8:11]
	v_mfma_f32_16x16x32_bf16 v[4:7], v[160:163], v[206:209], v[4:7]
	v_mfma_f32_16x16x32_bf16 v[0:3], v[168:171], v[206:209], v[0:3]
	s_setprio 0
	s_barrier
	s_add_i32 s6, s6, 2
	s_add_u32 s2, s2, 0x100
	s_addc_u32 s3, s3, 0
	s_cmp_gt_u32 s6, 5
	s_mov_b64 s[42:43], s[38:39]
	s_cbranch_scc0 .LBB0_1333
	s_nop 0
	s_nop 0
	s_nop 0
	s_nop 0
	s_nop 0
	s_nop 0
	s_nop 0
	s_nop 0
	s_nop 0
	s_and_b64 vcc, exec, s[14:15]
	s_cbranch_vccz .LBB0_1336
	s_barrier

.LBB0_1357:
	s_add_u32 s3, s14, s34
	s_addc_u32 s6, s15, s35
	s_add_u32 s3, s3, 0x100
	s_addc_u32 s6, s6, 0
	s_add_u32 s42, s57, s34
	s_addc_u32 s43, s58, s35
	s_add_i32 s59, 0, 0x10000
	s_cmpk_eq_i32 s34, 0x2b00
	s_cselect_b32 s45, s23, s6
	s_cselect_b32 s44, s22, s3
	v_add_u32_e32 v146, s59, v144
	s_cselect_b32 s43, s25, s43
	s_cselect_b32 s42, s24, s42
	s_add_i32 s3, 0, 0x14000
	ds_read_b128 v[154:157], v146
	ds_read_b128 v[158:161], v146 offset:1024
	ds_read_b128 v[162:165], v146 offset:2048
	ds_read_b128 v[166:169], v146 offset:3072
	v_add_u32_e32 v146, s3, v144
	ds_read_b128 v[174:177], v146
	ds_read_b128 v[178:181], v146 offset:1024
	ds_read_b128 v[182:185], v146 offset:2048
	ds_read_b128 v[186:189], v146 offset:3072
	v_lshl_add_u64 v[146:147], v[140:141], 0, s[34:35]
	s_add_i32 m0, s17, 0xc000
	ds_read_b128 v[190:193], v145
	ds_read_b128 v[202:205], v145 offset:1024
	ds_read_b128 v[206:209], v145 offset:2048
	ds_read_b128 v[214:217], v145 offset:3072
	ds_read_b128 v[218:221], v145 offset:4096
	ds_read_b128 v[222:225], v145 offset:5120
	ds_read_b128 v[226:229], v145 offset:6144
	ds_read_b128 v[230:233], v145 offset:7168
	global_load_lds_dwordx4 v[146:147], off
	v_lshl_add_u64 v[146:147], v[142:143], 0, s[34:35]
	s_add_i32 m0, s17, 0xe000
	s_nop 0
	global_load_lds_dwordx4 v[146:147], off
	s_waitcnt vmcnt(8)
	s_waitcnt lgkmcnt(0)
	s_barrier
	s_setprio 1
	s_waitcnt lgkmcnt(0)
	v_mfma_f32_16x16x32_bf16 v[110:113], v[154:157], v[190:193], v[110:113]
	v_mfma_f32_16x16x32_bf16 v[106:109], v[162:165], v[190:193], v[106:109]
	v_mfma_f32_16x16x32_bf16 v[118:121], v[154:157], v[206:209], v[118:121]
	v_mfma_f32_16x16x32_bf16 v[114:117], v[162:165], v[206:209], v[114:117]
	v_mfma_f32_16x16x32_bf16 v[126:129], v[154:157], v[218:221], v[126:129]
	v_mfma_f32_16x16x32_bf16 v[122:125], v[162:165], v[218:221], v[122:125]
	v_mfma_f32_16x16x32_bf16 v[92:95], v[154:157], v[226:229], v[92:95]
	v_mfma_f32_16x16x32_bf16 v[88:91], v[162:165], v[226:229], v[88:91]
	v_mfma_f32_16x16x32_bf16 v[110:113], v[158:161], v[202:205], v[110:113]
	v_mfma_f32_16x16x32_bf16 v[106:109], v[166:169], v[202:205], v[106:109]
	v_mfma_f32_16x16x32_bf16 v[118:121], v[158:161], v[214:217], v[118:121]
	v_mfma_f32_16x16x32_bf16 v[114:117], v[166:169], v[214:217], v[114:117]
	v_mfma_f32_16x16x32_bf16 v[126:129], v[158:161], v[222:225], v[126:129]
	v_mfma_f32_16x16x32_bf16 v[122:125], v[166:169], v[222:225], v[122:125]
	v_mfma_f32_16x16x32_bf16 v[92:95], v[158:161], v[230:233], v[92:95]
	v_mfma_f32_16x16x32_bf16 v[88:91], v[166:169], v[230:233], v[88:91]
	s_setprio 0
	s_setprio 1
	v_mfma_f32_16x16x32_bf16 v[4:7], v[174:177], v[190:193], v[4:7]
	v_mfma_f32_16x16x32_bf16 v[0:3], v[182:185], v[190:193], v[0:3]
	v_mfma_f32_16x16x32_bf16 v[12:15], v[174:177], v[206:209], v[12:15]
	v_mfma_f32_16x16x32_bf16 v[8:11], v[182:185], v[206:209], v[8:11]
	v_mfma_f32_16x16x32_bf16 v[24:27], v[174:177], v[218:221], v[24:27]
	v_mfma_f32_16x16x32_bf16 v[20:23], v[182:185], v[218:221], v[20:23]
	v_mfma_f32_16x16x32_bf16 v[40:43], v[174:177], v[226:229], v[40:43]
	v_mfma_f32_16x16x32_bf16 v[36:39], v[182:185], v[226:229], v[36:39]
	v_mfma_f32_16x16x32_bf16 v[4:7], v[178:181], v[202:205], v[4:7]
	v_mfma_f32_16x16x32_bf16 v[0:3], v[186:189], v[202:205], v[0:3]
	v_mfma_f32_16x16x32_bf16 v[12:15], v[178:181], v[214:217], v[12:15]
	v_mfma_f32_16x16x32_bf16 v[8:11], v[186:189], v[214:217], v[8:11]
	v_mfma_f32_16x16x32_bf16 v[24:27], v[178:181], v[222:225], v[24:27]
	v_mfma_f32_16x16x32_bf16 v[20:23], v[186:189], v[222:225], v[20:23]
	v_mfma_f32_16x16x32_bf16 v[40:43], v[178:181], v[230:233], v[40:43]
	v_mfma_f32_16x16x32_bf16 v[36:39], v[186:189], v[230:233], v[36:39]
	s_setprio 0
	s_barrier
	s_add_i32 s6, s59, s5
	s_mov_b32 m0, s6
	ds_read_b128 v[190:193], v145 offset:16384
	ds_read_b128 v[202:205], v145 offset:17408
	ds_read_b128 v[206:209], v145 offset:18432
	ds_read_b128 v[214:217], v145 offset:19456
	ds_read_b128 v[218:221], v145 offset:20480
	ds_read_b128 v[222:225], v145 offset:21504
	ds_read_b128 v[226:229], v145 offset:22528
	ds_read_b128 v[230:233], v145 offset:23552
	global_load_lds_dwordx4 v96, s[42:43]
	s_add_i32 m0, s6, 0x2000
	s_add_u32 s60, s42, 0x160000
	s_addc_u32 s61, s43, 0
	s_add_i32 s3, s3, s5
	global_load_lds_dwordx4 v130, s[42:43]
	s_mov_b32 m0, s3
	s_nop 0
	global_load_lds_dwordx4 v96, s[60:61]
	s_add_i32 m0, s3, 0x2000
	s_nop 0
	global_load_lds_dwordx4 v130, s[60:61]
	s_mov_b32 m0, s17
	s_nop 0
	global_load_lds_dwordx4 v134, s[44:45]
	s_mov_b32 m0, s18
	s_nop 0
	global_load_lds_dwordx4 v132, s[44:45]
	s_waitcnt vmcnt(8)
	s_waitcnt lgkmcnt(0)
	s_barrier
	s_setprio 1
	s_waitcnt lgkmcnt(0)
	v_mfma_f32_16x16x32_bf16 v[102:105], v[154:157], v[190:193], v[102:105]
	v_mfma_f32_16x16x32_bf16 v[98:101], v[162:165], v[190:193], v[98:101]
	v_mfma_f32_16x16x32_bf16 v[84:87], v[154:157], v[206:209], v[84:87]
	v_mfma_f32_16x16x32_bf16 v[80:83], v[162:165], v[206:209], v[80:83]
	v_mfma_f32_16x16x32_bf16 v[68:71], v[154:157], v[218:221], v[68:71]
	v_mfma_f32_16x16x32_bf16 v[64:67], v[162:165], v[218:221], v[64:67]
	v_mfma_f32_16x16x32_bf16 v[44:47], v[154:157], v[226:229], v[44:47]
	v_mfma_f32_16x16x32_bf16 v[32:35], v[162:165], v[226:229], v[32:35]
	v_mfma_f32_16x16x32_bf16 v[102:105], v[158:161], v[202:205], v[102:105]
	v_mfma_f32_16x16x32_bf16 v[98:101], v[166:169], v[202:205], v[98:101]
	v_mfma_f32_16x16x32_bf16 v[84:87], v[158:161], v[214:217], v[84:87]
	v_mfma_f32_16x16x32_bf16 v[80:83], v[166:169], v[214:217], v[80:83]
	v_mfma_f32_16x16x32_bf16 v[68:71], v[158:161], v[222:225], v[68:71]
	v_mfma_f32_16x16x32_bf16 v[64:67], v[166:169], v[222:225], v[64:67]
	v_mfma_f32_16x16x32_bf16 v[44:47], v[158:161], v[230:233], v[44:47]
	v_mfma_f32_16x16x32_bf16 v[32:35], v[166:169], v[230:233], v[32:35]
	s_setprio 0
	s_setprio 1
	v_mfma_f32_16x16x32_bf16 v[60:63], v[174:177], v[190:193], v[60:63]
	v_mfma_f32_16x16x32_bf16 v[56:59], v[182:185], v[190:193], v[56:59]
	v_mfma_f32_16x16x32_bf16 v[76:79], v[174:177], v[206:209], v[76:79]
	v_mfma_f32_16x16x32_bf16 v[72:75], v[182:185], v[206:209], v[72:75]
	v_mfma_f32_16x16x32_bf16 v[52:55], v[174:177], v[218:221], v[52:55]
	v_mfma_f32_16x16x32_bf16 v[48:51], v[182:185], v[218:221], v[48:51]
	v_mfma_f32_16x16x32_bf16 v[28:31], v[174:177], v[226:229], v[28:31]
	v_mfma_f32_16x16x32_bf16 v[16:19], v[182:185], v[226:229], v[16:19]
	v_mfma_f32_16x16x32_bf16 v[60:63], v[178:181], v[202:205], v[60:63]
	v_mfma_f32_16x16x32_bf16 v[56:59], v[186:189], v[202:205], v[56:59]
	v_mfma_f32_16x16x32_bf16 v[76:79], v[178:181], v[214:217], v[76:79]
	v_mfma_f32_16x16x32_bf16 v[72:75], v[186:189], v[214:217], v[72:75]
	v_mfma_f32_16x16x32_bf16 v[52:55], v[178:181], v[222:225], v[52:55]
	v_mfma_f32_16x16x32_bf16 v[48:51], v[186:189], v[222:225], v[48:51]
	v_mfma_f32_16x16x32_bf16 v[28:31], v[178:181], v[230:233], v[28:31]
	v_mfma_f32_16x16x32_bf16 v[16:19], v[186:189], v[230:233], v[16:19]
	s_setprio 0
	s_barrier
	s_add_i32 s3, 0, 0x18000
	v_add_u32_e32 v149, s3, v144
	s_add_i32 s6, 0, 0x1c000
	ds_read_b128 v[154:157], v149
	ds_read_b128 v[158:161], v149 offset:1024
	ds_read_b128 v[162:165], v149 offset:2048
	ds_read_b128 v[166:169], v149 offset:3072
	v_add_u32_e32 v149, s6, v144
	ds_read_b128 v[174:177], v149
	ds_read_b128 v[178:181], v149 offset:1024
	ds_read_b128 v[182:185], v149 offset:2048
	ds_read_b128 v[186:189], v149 offset:3072
	s_add_u32 s44, s44, 0x160000
	s_addc_u32 s45, s45, 0
	s_mov_b32 m0, s19
	ds_read_b128 v[190:193], v145 offset:32768
	ds_read_b128 v[202:205], v145 offset:33792
	ds_read_b128 v[206:209], v145 offset:34816
	ds_read_b128 v[214:217], v145 offset:35840
	ds_read_b128 v[218:221], v145 offset:36864
	ds_read_b128 v[222:225], v145 offset:37888
	ds_read_b128 v[226:229], v145 offset:38912
	ds_read_b128 v[230:233], v145 offset:39936
	global_load_lds_dwordx4 v134, s[44:45]
	s_mov_b32 m0, s20
	s_nop 0
	global_load_lds_dwordx4 v132, s[44:45]
	s_waitcnt vmcnt(8)
	s_waitcnt lgkmcnt(0)
	s_barrier
	s_setprio 1
	s_waitcnt lgkmcnt(0)
	v_mfma_f32_16x16x32_bf16 v[110:113], v[154:157], v[190:193], v[110:113]
	v_mfma_f32_16x16x32_bf16 v[106:109], v[162:165], v[190:193], v[106:109]
	v_mfma_f32_16x16x32_bf16 v[118:121], v[154:157], v[206:209], v[118:121]
	v_mfma_f32_16x16x32_bf16 v[114:117], v[162:165], v[206:209], v[114:117]
	v_mfma_f32_16x16x32_bf16 v[126:129], v[154:157], v[218:221], v[126:129]
	v_mfma_f32_16x16x32_bf16 v[122:125], v[162:165], v[218:221], v[122:125]
	v_mfma_f32_16x16x32_bf16 v[92:95], v[154:157], v[226:229], v[92:95]
	v_mfma_f32_16x16x32_bf16 v[88:91], v[162:165], v[226:229], v[88:91]
	v_mfma_f32_16x16x32_bf16 v[110:113], v[158:161], v[202:205], v[110:113]
	v_mfma_f32_16x16x32_bf16 v[106:109], v[166:169], v[202:205], v[106:109]
	v_mfma_f32_16x16x32_bf16 v[118:121], v[158:161], v[214:217], v[118:121]
	v_mfma_f32_16x16x32_bf16 v[114:117], v[166:169], v[214:217], v[114:117]
	v_mfma_f32_16x16x32_bf16 v[126:129], v[158:161], v[222:225], v[126:129]
	v_mfma_f32_16x16x32_bf16 v[122:125], v[166:169], v[222:225], v[122:125]
	v_mfma_f32_16x16x32_bf16 v[92:95], v[158:161], v[230:233], v[92:95]
	v_mfma_f32_16x16x32_bf16 v[88:91], v[166:169], v[230:233], v[88:91]
	s_setprio 0
	s_setprio 1
	v_mfma_f32_16x16x32_bf16 v[4:7], v[174:177], v[190:193], v[4:7]
	v_mfma_f32_16x16x32_bf16 v[0:3], v[182:185], v[190:193], v[0:3]
	v_mfma_f32_16x16x32_bf16 v[12:15], v[174:177], v[206:209], v[12:15]
	v_mfma_f32_16x16x32_bf16 v[8:11], v[182:185], v[206:209], v[8:11]
	v_mfma_f32_16x16x32_bf16 v[24:27], v[174:177], v[218:221], v[24:27]
	v_mfma_f32_16x16x32_bf16 v[20:23], v[182:185], v[218:221], v[20:23]
	v_mfma_f32_16x16x32_bf16 v[40:43], v[174:177], v[226:229], v[40:43]
	v_mfma_f32_16x16x32_bf16 v[36:39], v[182:185], v[226:229], v[36:39]
	v_mfma_f32_16x16x32_bf16 v[4:7], v[178:181], v[202:205], v[4:7]
	v_mfma_f32_16x16x32_bf16 v[0:3], v[186:189], v[202:205], v[0:3]
	v_mfma_f32_16x16x32_bf16 v[12:15], v[178:181], v[214:217], v[12:15]
	v_mfma_f32_16x16x32_bf16 v[8:11], v[186:189], v[214:217], v[8:11]
	v_mfma_f32_16x16x32_bf16 v[24:27], v[178:181], v[222:225], v[24:27]
	v_mfma_f32_16x16x32_bf16 v[20:23], v[186:189], v[222:225], v[20:23]
	v_mfma_f32_16x16x32_bf16 v[40:43], v[178:181], v[230:233], v[40:43]
	v_mfma_f32_16x16x32_bf16 v[36:39], v[186:189], v[230:233], v[36:39]
	s_setprio 0
	s_barrier
	s_add_i32 s3, s3, s5
	s_mov_b32 m0, s3
	ds_read_b128 v[190:193], v145 offset:49152
	ds_read_b128 v[202:205], v145 offset:50176
	ds_read_b128 v[206:209], v145 offset:51200
	ds_read_b128 v[214:217], v145 offset:52224
	ds_read_b128 v[218:221], v145 offset:53248
	ds_read_b128 v[222:225], v145 offset:54272
	ds_read_b128 v[226:229], v145 offset:55296
	ds_read_b128 v[230:233], v145 offset:56320
	s_add_u32 s100, s42, 0x80
	s_addc_u32 s101, s43, 0
	global_load_lds_dwordx4 v96, s[100:101]
	s_add_i32 m0, s3, 0x2000
	s_add_u32 s42, s42, 0x160080
	s_addc_u32 s43, s43, 0
	s_add_i32 s3, s6, s5
	global_load_lds_dwordx4 v130, s[100:101]
	s_mov_b32 m0, s3
	s_nop 0
	global_load_lds_dwordx4 v96, s[42:43]
	s_add_i32 m0, s3, 0x2000
	s_nop 0
	global_load_lds_dwordx4 v130, s[42:43]
	s_mov_b32 m0, s37
	s_nop 0
	s_sub_u32 s100, s44, 0x15ff80
	s_subb_u32 s101, s45, 0
	global_load_lds_dwordx4 v134, s[100:101]
	s_mov_b32 m0, s52
	s_nop 0
	global_load_lds_dwordx4 v132, s[100:101]
	s_waitcnt vmcnt(8)
	s_waitcnt lgkmcnt(0)
	s_barrier
	s_setprio 1
	s_waitcnt lgkmcnt(0)
	v_mfma_f32_16x16x32_bf16 v[102:105], v[154:157], v[190:193], v[102:105]
	v_mfma_f32_16x16x32_bf16 v[98:101], v[162:165], v[190:193], v[98:101]
	v_mfma_f32_16x16x32_bf16 v[84:87], v[154:157], v[206:209], v[84:87]
	v_mfma_f32_16x16x32_bf16 v[80:83], v[162:165], v[206:209], v[80:83]
	v_mfma_f32_16x16x32_bf16 v[68:71], v[154:157], v[218:221], v[68:71]
	v_mfma_f32_16x16x32_bf16 v[64:67], v[162:165], v[218:221], v[64:67]
	v_mfma_f32_16x16x32_bf16 v[44:47], v[154:157], v[226:229], v[44:47]
	v_mfma_f32_16x16x32_bf16 v[32:35], v[162:165], v[226:229], v[32:35]
	v_mfma_f32_16x16x32_bf16 v[102:105], v[158:161], v[202:205], v[102:105]
	v_mfma_f32_16x16x32_bf16 v[98:101], v[166:169], v[202:205], v[98:101]
	v_mfma_f32_16x16x32_bf16 v[84:87], v[158:161], v[214:217], v[84:87]
	v_mfma_f32_16x16x32_bf16 v[80:83], v[166:169], v[214:217], v[80:83]
	v_mfma_f32_16x16x32_bf16 v[68:71], v[158:161], v[222:225], v[68:71]
	v_mfma_f32_16x16x32_bf16 v[64:67], v[166:169], v[222:225], v[64:67]
	v_mfma_f32_16x16x32_bf16 v[44:47], v[158:161], v[230:233], v[44:47]
	v_mfma_f32_16x16x32_bf16 v[32:35], v[166:169], v[230:233], v[32:35]
	s_setprio 0
	s_setprio 1
	v_mfma_f32_16x16x32_bf16 v[60:63], v[174:177], v[190:193], v[60:63]
	v_mfma_f32_16x16x32_bf16 v[56:59], v[182:185], v[190:193], v[56:59]
	v_mfma_f32_16x16x32_bf16 v[76:79], v[174:177], v[206:209], v[76:79]
	v_mfma_f32_16x16x32_bf16 v[72:75], v[182:185], v[206:209], v[72:75]
	v_mfma_f32_16x16x32_bf16 v[52:55], v[174:177], v[218:221], v[52:55]
	v_mfma_f32_16x16x32_bf16 v[48:51], v[182:185], v[218:221], v[48:51]
	v_mfma_f32_16x16x32_bf16 v[28:31], v[174:177], v[226:229], v[28:31]
	v_mfma_f32_16x16x32_bf16 v[16:19], v[182:185], v[226:229], v[16:19]
	v_mfma_f32_16x16x32_bf16 v[60:63], v[178:181], v[202:205], v[60:63]
	v_mfma_f32_16x16x32_bf16 v[56:59], v[186:189], v[202:205], v[56:59]
	v_mfma_f32_16x16x32_bf16 v[76:79], v[178:181], v[214:217], v[76:79]
	v_mfma_f32_16x16x32_bf16 v[72:75], v[186:189], v[214:217], v[72:75]
	v_mfma_f32_16x16x32_bf16 v[52:55], v[178:181], v[222:225], v[52:55]
	v_mfma_f32_16x16x32_bf16 v[48:51], v[186:189], v[222:225], v[48:51]
	v_mfma_f32_16x16x32_bf16 v[28:31], v[178:181], v[230:233], v[28:31]
	v_mfma_f32_16x16x32_bf16 v[16:19], v[186:189], v[230:233], v[16:19]
	s_setprio 0
	s_barrier
	s_add_i32 s2, s2, 2
	s_add_u32 s34, s34, 0x100
	s_addc_u32 s35, s35, 0
	s_cmpk_gt_u32 s2, 0x55
	s_cbranch_scc0 .LBB0_1357
	s_nop 0
	s_nop 0
	s_nop 0
	s_nop 0
	s_nop 0
	s_and_b64 vcc, exec, s[12:13]
	s_cbranch_vccz .LBB0_1360
	s_barrier

.LBB0_1412:
	s_add_u32 s2, s24, 0x100
	v_mov_b32_e32 v0, 0
	s_addc_u32 s3, s25, 0
	s_mov_b32 s6, -2
	v_mov_b32_e32 v1, v0
	v_mov_b32_e32 v2, v0
	v_mov_b32_e32 v3, v0
	v_mov_b32_e32 v4, v0
	v_mov_b32_e32 v5, v0
	v_mov_b32_e32 v6, v0
	v_mov_b32_e32 v7, v0
	v_mov_b32_e32 v8, v0
	v_mov_b32_e32 v9, v0
	v_mov_b32_e32 v10, v0
	v_mov_b32_e32 v11, v0
	v_mov_b32_e32 v20, v0
	v_mov_b32_e32 v21, v0
	v_mov_b32_e32 v22, v0
	v_mov_b32_e32 v23, v0
	v_mov_b32_e32 v24, v0
	v_mov_b32_e32 v25, v0
	v_mov_b32_e32 v26, v0
	v_mov_b32_e32 v27, v0
	v_mov_b32_e32 v36, v0
	v_mov_b32_e32 v37, v0
	v_mov_b32_e32 v38, v0
	v_mov_b32_e32 v39, v0
	v_mov_b32_e32 v40, v0
	v_mov_b32_e32 v41, v0
	v_mov_b32_e32 v42, v0
	v_mov_b32_e32 v43, v0
	v_mov_b32_e32 v52, v0
	v_mov_b32_e32 v53, v0
	v_mov_b32_e32 v54, v0
	v_mov_b32_e32 v55, v0
	v_mov_b32_e32 v12, v0
	v_mov_b32_e32 v13, v0
	v_mov_b32_e32 v14, v0
	v_mov_b32_e32 v15, v0
	v_mov_b32_e32 v16, v0
	v_mov_b32_e32 v17, v0
	v_mov_b32_e32 v18, v0
	v_mov_b32_e32 v19, v0
	v_mov_b32_e32 v28, v0
	v_mov_b32_e32 v29, v0
	v_mov_b32_e32 v30, v0
	v_mov_b32_e32 v31, v0
	v_mov_b32_e32 v32, v0
	v_mov_b32_e32 v33, v0
	v_mov_b32_e32 v34, v0
	v_mov_b32_e32 v35, v0
	v_mov_b32_e32 v44, v0
	v_mov_b32_e32 v45, v0
	v_mov_b32_e32 v46, v0
	v_mov_b32_e32 v47, v0
	v_mov_b32_e32 v48, v0
	v_mov_b32_e32 v49, v0
	v_mov_b32_e32 v50, v0
	v_mov_b32_e32 v51, v0
	v_mov_b32_e32 v56, v0
	v_mov_b32_e32 v57, v0
	v_mov_b32_e32 v58, v0
	v_mov_b32_e32 v59, v0
	v_mov_b32_e32 v60, v0
	v_mov_b32_e32 v61, v0
	v_mov_b32_e32 v62, v0
	v_mov_b32_e32 v63, v0
	v_mov_b32_e32 v64, v0
	v_mov_b32_e32 v65, v0
	v_mov_b32_e32 v66, v0
	v_mov_b32_e32 v67, v0
	v_mov_b32_e32 v68, v0
	v_mov_b32_e32 v69, v0
	v_mov_b32_e32 v70, v0
	v_mov_b32_e32 v71, v0
	v_mov_b32_e32 v72, v0
	v_mov_b32_e32 v73, v0
	v_mov_b32_e32 v74, v0
	v_mov_b32_e32 v75, v0
	v_mov_b32_e32 v84, v0
	v_mov_b32_e32 v85, v0
	v_mov_b32_e32 v86, v0
	v_mov_b32_e32 v87, v0
	v_mov_b32_e32 v88, v0
	v_mov_b32_e32 v89, v0
	v_mov_b32_e32 v90, v0
	v_mov_b32_e32 v91, v0
	v_mov_b32_e32 v102, v0
	v_mov_b32_e32 v103, v0
	v_mov_b32_e32 v104, v0
	v_mov_b32_e32 v105, v0
	v_mov_b32_e32 v106, v0
	v_mov_b32_e32 v107, v0
	v_mov_b32_e32 v108, v0
	v_mov_b32_e32 v109, v0
	v_mov_b32_e32 v118, v0
	v_mov_b32_e32 v119, v0
	v_mov_b32_e32 v120, v0
	v_mov_b32_e32 v121, v0
	v_mov_b32_e32 v76, v0
	v_mov_b32_e32 v77, v0
	v_mov_b32_e32 v78, v0
	v_mov_b32_e32 v79, v0
	v_mov_b32_e32 v80, v0
	v_mov_b32_e32 v81, v0
	v_mov_b32_e32 v82, v0
	v_mov_b32_e32 v83, v0
	v_mov_b32_e32 v92, v0
	v_mov_b32_e32 v93, v0
	v_mov_b32_e32 v94, v0
	v_mov_b32_e32 v95, v0
	v_mov_b32_e32 v98, v0
	v_mov_b32_e32 v99, v0
	v_mov_b32_e32 v100, v0
	v_mov_b32_e32 v101, v0
	v_mov_b32_e32 v110, v0
	v_mov_b32_e32 v111, v0
	v_mov_b32_e32 v112, v0
	v_mov_b32_e32 v113, v0
	v_mov_b32_e32 v114, v0
	v_mov_b32_e32 v115, v0
	v_mov_b32_e32 v116, v0
	v_mov_b32_e32 v117, v0
	v_mov_b32_e32 v122, v0
	v_mov_b32_e32 v123, v0
	v_mov_b32_e32 v124, v0
	v_mov_b32_e32 v125, v0
	v_mov_b32_e32 v126, v0
	v_mov_b32_e32 v127, v0
	v_mov_b32_e32 v128, v0
	v_mov_b32_e32 v129, v0
	s_nop 0
	s_nop 0
	s_nop 0
	s_nop 0
.LBB0_1413:
	s_add_u32 s24, s22, 0x100
	s_addc_u32 s25, s23, 0
	s_add_i32 s45, 0, 0x10000
	s_cmpk_eq_i32 s6, 0x54
	s_cselect_b32 s39, s13, s25
	s_cselect_b32 s38, s12, s24
	s_cselect_b32 s35, s15, s3
	s_cselect_b32 s34, s14, s2
	s_add_i32 s46, 0, 0x14000
	v_add_u32_e32 v142, s45, v155
	v_add_u32_e32 v152, s46, v155
	ds_read_b128 v[130:133], v142
	ds_read_b128 v[134:137], v142 offset:1024
	ds_read_b128 v[138:141], v142 offset:2048
	ds_read_b128 v[142:145], v142 offset:3072
	ds_read_b128 v[158:161], v152
	ds_read_b128 v[162:165], v152 offset:1024
	ds_read_b128 v[166:169], v152 offset:2048
	ds_read_b128 v[170:173], v152 offset:3072
	s_add_i32 m0, s5, 0xc000
	ds_read_b128 v[174:177], v157
	ds_read_b128 v[178:181], v157 offset:1024
	ds_read_b128 v[182:185], v157 offset:2048
	ds_read_b128 v[186:189], v157 offset:3072
	ds_read_b128 v[190:193], v157 offset:4096
	ds_read_b128 v[202:205], v157 offset:5120
	ds_read_b128 v[206:209], v157 offset:6144
	ds_read_b128 v[214:217], v157 offset:7168
	global_load_lds_dwordx4 v148, s[22:23]
	s_add_i32 m0, s5, 0xe000
	s_nop 0
	global_load_lds_dwordx4 v150, s[22:23]
	s_waitcnt vmcnt(8)
	s_waitcnt lgkmcnt(0)
	s_barrier
	s_setprio 1
	s_waitcnt lgkmcnt(0)
	v_mfma_f32_16x16x32_bf16 v[126:129], v[130:133], v[174:177], v[126:129]
	v_mfma_f32_16x16x32_bf16 v[122:125], v[138:141], v[174:177], v[122:125]
	v_mfma_f32_16x16x32_bf16 v[114:117], v[130:133], v[182:185], v[114:117]
	v_mfma_f32_16x16x32_bf16 v[110:113], v[138:141], v[182:185], v[110:113]
	v_mfma_f32_16x16x32_bf16 v[98:101], v[130:133], v[190:193], v[98:101]
	v_mfma_f32_16x16x32_bf16 v[92:95], v[138:141], v[190:193], v[92:95]
	v_mfma_f32_16x16x32_bf16 v[80:83], v[130:133], v[206:209], v[80:83]
	v_mfma_f32_16x16x32_bf16 v[76:79], v[138:141], v[206:209], v[76:79]
	v_mfma_f32_16x16x32_bf16 v[126:129], v[134:137], v[178:181], v[126:129]
	v_mfma_f32_16x16x32_bf16 v[122:125], v[142:145], v[178:181], v[122:125]
	v_mfma_f32_16x16x32_bf16 v[114:117], v[134:137], v[186:189], v[114:117]
	v_mfma_f32_16x16x32_bf16 v[110:113], v[142:145], v[186:189], v[110:113]
	v_mfma_f32_16x16x32_bf16 v[98:101], v[134:137], v[202:205], v[98:101]
	v_mfma_f32_16x16x32_bf16 v[92:95], v[142:145], v[202:205], v[92:95]
	v_mfma_f32_16x16x32_bf16 v[80:83], v[134:137], v[214:217], v[80:83]
	v_mfma_f32_16x16x32_bf16 v[76:79], v[142:145], v[214:217], v[76:79]
	s_setprio 0
	s_setprio 1
	v_mfma_f32_16x16x32_bf16 v[118:121], v[158:161], v[174:177], v[118:121]
	v_mfma_f32_16x16x32_bf16 v[106:109], v[166:169], v[174:177], v[106:109]
	v_mfma_f32_16x16x32_bf16 v[102:105], v[158:161], v[182:185], v[102:105]
	v_mfma_f32_16x16x32_bf16 v[88:91], v[166:169], v[182:185], v[88:91]
	v_mfma_f32_16x16x32_bf16 v[84:87], v[158:161], v[190:193], v[84:87]
	v_mfma_f32_16x16x32_bf16 v[72:75], v[166:169], v[190:193], v[72:75]
	v_mfma_f32_16x16x32_bf16 v[68:71], v[158:161], v[206:209], v[68:71]
	v_mfma_f32_16x16x32_bf16 v[64:67], v[166:169], v[206:209], v[64:67]
	v_mfma_f32_16x16x32_bf16 v[118:121], v[162:165], v[178:181], v[118:121]
	v_mfma_f32_16x16x32_bf16 v[106:109], v[170:173], v[178:181], v[106:109]
	v_mfma_f32_16x16x32_bf16 v[102:105], v[162:165], v[186:189], v[102:105]
	v_mfma_f32_16x16x32_bf16 v[88:91], v[170:173], v[186:189], v[88:91]
	v_mfma_f32_16x16x32_bf16 v[84:87], v[162:165], v[202:205], v[84:87]
	v_mfma_f32_16x16x32_bf16 v[72:75], v[170:173], v[202:205], v[72:75]
	v_mfma_f32_16x16x32_bf16 v[68:71], v[162:165], v[214:217], v[68:71]
	v_mfma_f32_16x16x32_bf16 v[64:67], v[170:173], v[214:217], v[64:67]
	s_setprio 0
	s_barrier
	s_add_i32 s22, s45, s4
	s_mov_b32 m0, s22
	ds_read_b128 v[174:177], v157 offset:16384
	ds_read_b128 v[178:181], v157 offset:17408
	ds_read_b128 v[182:185], v157 offset:18432
	ds_read_b128 v[186:189], v157 offset:19456
	ds_read_b128 v[190:193], v157 offset:20480
	ds_read_b128 v[202:205], v157 offset:21504
	ds_read_b128 v[206:209], v157 offset:22528
	ds_read_b128 v[214:217], v157 offset:23552
	global_load_lds_dwordx4 v96, s[34:35]
	s_add_i32 m0, s22, 0x2000
	s_add_u32 s22, s34, 0x160000
	s_addc_u32 s23, s35, 0
	s_add_i32 s45, s46, s4
	global_load_lds_dwordx4 v146, s[34:35]
	s_mov_b32 m0, s45
	s_nop 0
	global_load_lds_dwordx4 v96, s[22:23]
	s_add_i32 m0, s45, 0x2000
	s_nop 0
	global_load_lds_dwordx4 v146, s[22:23]
	s_mov_b32 m0, s5
	s_nop 0
	global_load_lds_dwordx4 v96, s[38:39]
	s_mov_b32 m0, s17
	s_nop 0
	global_load_lds_dwordx4 v146, s[38:39]
	s_waitcnt vmcnt(8)
	s_waitcnt lgkmcnt(0)
	s_barrier
	s_setprio 1
	s_waitcnt lgkmcnt(0)
	v_mfma_f32_16x16x32_bf16 v[60:63], v[130:133], v[174:177], v[60:63]
	v_mfma_f32_16x16x32_bf16 v[56:59], v[138:141], v[174:177], v[56:59]
	v_mfma_f32_16x16x32_bf16 v[48:51], v[130:133], v[182:185], v[48:51]
	v_mfma_f32_16x16x32_bf16 v[44:47], v[138:141], v[182:185], v[44:47]
	v_mfma_f32_16x16x32_bf16 v[32:35], v[130:133], v[190:193], v[32:35]
	v_mfma_f32_16x16x32_bf16 v[28:31], v[138:141], v[190:193], v[28:31]
	v_mfma_f32_16x16x32_bf16 v[16:19], v[130:133], v[206:209], v[16:19]
	v_mfma_f32_16x16x32_bf16 v[12:15], v[138:141], v[206:209], v[12:15]
	v_mfma_f32_16x16x32_bf16 v[60:63], v[134:137], v[178:181], v[60:63]
	v_mfma_f32_16x16x32_bf16 v[56:59], v[142:145], v[178:181], v[56:59]
	v_mfma_f32_16x16x32_bf16 v[48:51], v[134:137], v[186:189], v[48:51]
	v_mfma_f32_16x16x32_bf16 v[44:47], v[142:145], v[186:189], v[44:47]
	v_mfma_f32_16x16x32_bf16 v[32:35], v[134:137], v[202:205], v[32:35]
	v_mfma_f32_16x16x32_bf16 v[28:31], v[142:145], v[202:205], v[28:31]
	v_mfma_f32_16x16x32_bf16 v[16:19], v[134:137], v[214:217], v[16:19]
	v_mfma_f32_16x16x32_bf16 v[12:15], v[142:145], v[214:217], v[12:15]
	s_setprio 0
	s_setprio 1
	v_mfma_f32_16x16x32_bf16 v[52:55], v[158:161], v[174:177], v[52:55]
	v_mfma_f32_16x16x32_bf16 v[40:43], v[166:169], v[174:177], v[40:43]
	v_mfma_f32_16x16x32_bf16 v[36:39], v[158:161], v[182:185], v[36:39]
	v_mfma_f32_16x16x32_bf16 v[24:27], v[166:169], v[182:185], v[24:27]
	v_mfma_f32_16x16x32_bf16 v[20:23], v[158:161], v[190:193], v[20:23]
	v_mfma_f32_16x16x32_bf16 v[8:11], v[166:169], v[190:193], v[8:11]
	v_mfma_f32_16x16x32_bf16 v[4:7], v[158:161], v[206:209], v[4:7]
	v_mfma_f32_16x16x32_bf16 v[0:3], v[166:169], v[206:209], v[0:3]
	v_mfma_f32_16x16x32_bf16 v[52:55], v[162:165], v[178:181], v[52:55]
	v_mfma_f32_16x16x32_bf16 v[40:43], v[170:173], v[178:181], v[40:43]
	v_mfma_f32_16x16x32_bf16 v[36:39], v[162:165], v[186:189], v[36:39]
	v_mfma_f32_16x16x32_bf16 v[24:27], v[170:173], v[186:189], v[24:27]
	v_mfma_f32_16x16x32_bf16 v[20:23], v[162:165], v[202:205], v[20:23]
	v_mfma_f32_16x16x32_bf16 v[8:11], v[170:173], v[202:205], v[8:11]
	v_mfma_f32_16x16x32_bf16 v[4:7], v[162:165], v[214:217], v[4:7]
	v_mfma_f32_16x16x32_bf16 v[0:3], v[170:173], v[214:217], v[0:3]
	s_setprio 0
	s_barrier
	s_add_i32 s45, 0, 0x18000
	s_add_i32 s46, 0, 0x1c000
	v_add_u32_e32 v142, s45, v155
	v_add_u32_e32 v170, s46, v155
	ds_read_b128 v[130:133], v142
	ds_read_b128 v[134:137], v142 offset:1024
	ds_read_b128 v[138:141], v142 offset:2048
	ds_read_b128 v[142:145], v142 offset:3072
	ds_read_b128 v[158:161], v170
	ds_read_b128 v[162:165], v170 offset:1024
	ds_read_b128 v[166:169], v170 offset:2048
	ds_read_b128 v[170:173], v170 offset:3072
	s_add_u32 s22, s38, 0x160000
	s_addc_u32 s23, s39, 0
	s_mov_b32 m0, s18
	ds_read_b128 v[174:177], v157 offset:32768
	ds_read_b128 v[178:181], v157 offset:33792
	ds_read_b128 v[182:185], v157 offset:34816
	ds_read_b128 v[186:189], v157 offset:35840
	ds_read_b128 v[190:193], v157 offset:36864
	ds_read_b128 v[202:205], v157 offset:37888
	ds_read_b128 v[206:209], v157 offset:38912
	ds_read_b128 v[214:217], v157 offset:39936
	global_load_lds_dwordx4 v96, s[22:23]
	s_mov_b32 m0, s19
	s_nop 0
	global_load_lds_dwordx4 v146, s[22:23]
	s_waitcnt vmcnt(8)
	s_waitcnt lgkmcnt(0)
	s_barrier
	s_setprio 1
	s_waitcnt lgkmcnt(0)
	v_mfma_f32_16x16x32_bf16 v[126:129], v[130:133], v[174:177], v[126:129]
	v_mfma_f32_16x16x32_bf16 v[122:125], v[138:141], v[174:177], v[122:125]
	v_mfma_f32_16x16x32_bf16 v[114:117], v[130:133], v[182:185], v[114:117]
	v_mfma_f32_16x16x32_bf16 v[110:113], v[138:141], v[182:185], v[110:113]
	v_mfma_f32_16x16x32_bf16 v[98:101], v[130:133], v[190:193], v[98:101]
	v_mfma_f32_16x16x32_bf16 v[92:95], v[138:141], v[190:193], v[92:95]
	v_mfma_f32_16x16x32_bf16 v[80:83], v[130:133], v[206:209], v[80:83]
	v_mfma_f32_16x16x32_bf16 v[76:79], v[138:141], v[206:209], v[76:79]
	v_mfma_f32_16x16x32_bf16 v[126:129], v[134:137], v[178:181], v[126:129]
	v_mfma_f32_16x16x32_bf16 v[122:125], v[142:145], v[178:181], v[122:125]
	v_mfma_f32_16x16x32_bf16 v[114:117], v[134:137], v[186:189], v[114:117]
	v_mfma_f32_16x16x32_bf16 v[110:113], v[142:145], v[186:189], v[110:113]
	v_mfma_f32_16x16x32_bf16 v[98:101], v[134:137], v[202:205], v[98:101]
	v_mfma_f32_16x16x32_bf16 v[92:95], v[142:145], v[202:205], v[92:95]
	v_mfma_f32_16x16x32_bf16 v[80:83], v[134:137], v[214:217], v[80:83]
	v_mfma_f32_16x16x32_bf16 v[76:79], v[142:145], v[214:217], v[76:79]
	s_setprio 0
	s_setprio 1
	v_mfma_f32_16x16x32_bf16 v[118:121], v[158:161], v[174:177], v[118:121]
	v_mfma_f32_16x16x32_bf16 v[106:109], v[166:169], v[174:177], v[106:109]
	v_mfma_f32_16x16x32_bf16 v[102:105], v[158:161], v[182:185], v[102:105]
	v_mfma_f32_16x16x32_bf16 v[88:91], v[166:169], v[182:185], v[88:91]
	v_mfma_f32_16x16x32_bf16 v[84:87], v[158:161], v[190:193], v[84:87]
	v_mfma_f32_16x16x32_bf16 v[72:75], v[166:169], v[190:193], v[72:75]
	v_mfma_f32_16x16x32_bf16 v[68:71], v[158:161], v[206:209], v[68:71]
	v_mfma_f32_16x16x32_bf16 v[64:67], v[166:169], v[206:209], v[64:67]
	v_mfma_f32_16x16x32_bf16 v[118:121], v[162:165], v[178:181], v[118:121]
	v_mfma_f32_16x16x32_bf16 v[106:109], v[170:173], v[178:181], v[106:109]
	v_mfma_f32_16x16x32_bf16 v[102:105], v[162:165], v[186:189], v[102:105]
	v_mfma_f32_16x16x32_bf16 v[88:91], v[170:173], v[186:189], v[88:91]
	v_mfma_f32_16x16x32_bf16 v[84:87], v[162:165], v[202:205], v[84:87]
	v_mfma_f32_16x16x32_bf16 v[72:75], v[170:173], v[202:205], v[72:75]
	v_mfma_f32_16x16x32_bf16 v[68:71], v[162:165], v[214:217], v[68:71]
	v_mfma_f32_16x16x32_bf16 v[64:67], v[170:173], v[214:217], v[64:67]
	s_setprio 0
	s_barrier
	s_add_i32 s22, s45, s4
	s_mov_b32 m0, s22
	ds_read_b128 v[174:177], v157 offset:49152
	ds_read_b128 v[178:181], v157 offset:50176
	ds_read_b128 v[182:185], v157 offset:51200
	ds_read_b128 v[186:189], v157 offset:52224
	ds_read_b128 v[190:193], v157 offset:53248
	ds_read_b128 v[202:205], v157 offset:54272
	ds_read_b128 v[206:209], v157 offset:55296
	ds_read_b128 v[214:217], v157 offset:56320
	s_add_u32 s100, s34, 0x80
	s_addc_u32 s101, s35, 0
	global_load_lds_dwordx4 v96, s[100:101]
	s_add_i32 m0, s22, 0x2000
	s_add_u32 s22, s34, 0x160080
	s_addc_u32 s23, s35, 0
	s_add_i32 s34, s46, s4
	global_load_lds_dwordx4 v146, s[100:101]
	s_mov_b32 m0, s34
	s_nop 0
	global_load_lds_dwordx4 v96, s[22:23]
	s_add_i32 m0, s34, 0x2000
	s_nop 0
	global_load_lds_dwordx4 v146, s[22:23]
	s_mov_b32 m0, s20
	s_nop 0
	s_add_u32 s100, s38, 0x80
	s_addc_u32 s101, s39, 0
	global_load_lds_dwordx4 v96, s[100:101]
	s_mov_b32 m0, s36
	s_nop 0
	global_load_lds_dwordx4 v146, s[100:101]
	s_waitcnt vmcnt(8)
	s_waitcnt lgkmcnt(0)
	s_barrier
	s_setprio 1
	s_waitcnt lgkmcnt(0)
	v_mfma_f32_16x16x32_bf16 v[60:63], v[130:133], v[174:177], v[60:63]
	v_mfma_f32_16x16x32_bf16 v[56:59], v[138:141], v[174:177], v[56:59]
	v_mfma_f32_16x16x32_bf16 v[48:51], v[130:133], v[182:185], v[48:51]
	v_mfma_f32_16x16x32_bf16 v[44:47], v[138:141], v[182:185], v[44:47]
	v_mfma_f32_16x16x32_bf16 v[32:35], v[130:133], v[190:193], v[32:35]
	v_mfma_f32_16x16x32_bf16 v[28:31], v[138:141], v[190:193], v[28:31]
	v_mfma_f32_16x16x32_bf16 v[16:19], v[130:133], v[206:209], v[16:19]
	v_mfma_f32_16x16x32_bf16 v[12:15], v[138:141], v[206:209], v[12:15]
	v_mfma_f32_16x16x32_bf16 v[60:63], v[134:137], v[178:181], v[60:63]
	v_mfma_f32_16x16x32_bf16 v[56:59], v[142:145], v[178:181], v[56:59]
	v_mfma_f32_16x16x32_bf16 v[48:51], v[134:137], v[186:189], v[48:51]
	v_mfma_f32_16x16x32_bf16 v[44:47], v[142:145], v[186:189], v[44:47]
	v_mfma_f32_16x16x32_bf16 v[32:35], v[134:137], v[202:205], v[32:35]
	v_mfma_f32_16x16x32_bf16 v[28:31], v[142:145], v[202:205], v[28:31]
	v_mfma_f32_16x16x32_bf16 v[16:19], v[134:137], v[214:217], v[16:19]
	v_mfma_f32_16x16x32_bf16 v[12:15], v[142:145], v[214:217], v[12:15]
	s_setprio 0
	s_setprio 1
	v_mfma_f32_16x16x32_bf16 v[52:55], v[158:161], v[174:177], v[52:55]
	v_mfma_f32_16x16x32_bf16 v[40:43], v[166:169], v[174:177], v[40:43]
	v_mfma_f32_16x16x32_bf16 v[36:39], v[158:161], v[182:185], v[36:39]
	v_mfma_f32_16x16x32_bf16 v[24:27], v[166:169], v[182:185], v[24:27]
	v_mfma_f32_16x16x32_bf16 v[20:23], v[158:161], v[190:193], v[20:23]
	v_mfma_f32_16x16x32_bf16 v[8:11], v[166:169], v[190:193], v[8:11]
	v_mfma_f32_16x16x32_bf16 v[4:7], v[158:161], v[206:209], v[4:7]
	v_mfma_f32_16x16x32_bf16 v[0:3], v[166:169], v[206:209], v[0:3]
	v_mfma_f32_16x16x32_bf16 v[52:55], v[162:165], v[178:181], v[52:55]
	v_mfma_f32_16x16x32_bf16 v[40:43], v[170:173], v[178:181], v[40:43]
	v_mfma_f32_16x16x32_bf16 v[36:39], v[162:165], v[186:189], v[36:39]
	v_mfma_f32_16x16x32_bf16 v[24:27], v[170:173], v[186:189], v[24:27]
	v_mfma_f32_16x16x32_bf16 v[20:23], v[162:165], v[202:205], v[20:23]
	v_mfma_f32_16x16x32_bf16 v[8:11], v[170:173], v[202:205], v[8:11]
	v_mfma_f32_16x16x32_bf16 v[4:7], v[162:165], v[214:217], v[4:7]
	v_mfma_f32_16x16x32_bf16 v[0:3], v[170:173], v[214:217], v[0:3]
	s_setprio 0
	s_barrier
	s_add_i32 s6, s6, 2
	s_add_u32 s2, s2, 0x100
	s_addc_u32 s3, s3, 0
	s_cmpk_gt_u32 s6, 0x55
	s_mov_b64 s[22:23], s[24:25]
	s_cbranch_scc0 .LBB0_1413
	s_nop 0
	s_nop 0
	s_nop 0
	s_nop 0
	s_nop 0
	s_and_b64 vcc, exec, s[10:11]
	s_cbranch_vccz .LBB0_1416
	s_barrier
